# MFMA pairs with srcA (weight fragment) shared at pair boundaries, static prio
# speedup vs baseline: 1.0050x; 1.0047x over previous
.LBB0_175:
	s_add_i32 s29, s29, 2
	s_mov_b32 s44, s29
	s_ashr_i32 s45, s44, 31
	s_lshl_b64 s[82:83], s[44:45], 7
	s_add_u32 s45, s82, 0x100
	s_addc_u32 s81, s83, 0
	s_add_u32 s84, s42, s45
	s_addc_u32 s85, s43, s81
	s_add_u32 s86, s40, s45
	s_addc_u32 s81, s41, s81
	s_cmp_eq_u32 s44, 14
	s_cselect_b32 s45, s75, s85
	s_cselect_b32 s44, s76, s84
	s_cselect_b32 s85, s31, s81
	s_cselect_b32 s84, s74, s86
	s_add_u32 s82, s42, s82
	s_addc_u32 s83, s43, s83
	v_lshl_add_u64 v[212:213], s[82:83], 0, v[130:131]
	s_mov_b32 m0, s66
	v_lshl_add_u64 v[214:215], v[212:213], 0, s[22:23]
	global_load_lds_dwordx4 v[214:215], off
	v_lshl_add_u64 v[212:213], v[212:213], 0, s[24:25]
	s_mov_b32 m0, s67
	s_nop 0
	global_load_lds_dwordx4 v[212:213], off
	ds_read_b128 v[146:149], v141
	ds_read_b128 v[150:153], v141 offset:1024
	ds_read_b128 v[154:157], v141 offset:2048
	ds_read_b128 v[158:161], v141 offset:3072
	ds_read_b128 v[162:165], v142
	ds_read_b128 v[166:169], v142 offset:1024
	ds_read_b128 v[170:173], v142 offset:2048
	ds_read_b128 v[174:177], v142 offset:3072
	ds_read_b128 v[178:181], v143
	ds_read_b128 v[182:185], v143 offset:1024
	ds_read_b128 v[186:189], v143 offset:2048
	ds_read_b128 v[190:193], v143 offset:3072
	ds_read_b128 v[194:197], v143 offset:4096
	ds_read_b128 v[198:201], v143 offset:5120
	ds_read_b128 v[202:205], v143 offset:6144
	ds_read_b128 v[206:209], v143 offset:7168
	s_waitcnt vmcnt(8)
	s_waitcnt lgkmcnt(0)
	s_barrier
	s_waitcnt lgkmcnt(0)
	v_mfma_f32_16x16x32_bf16 v[124:127], v[146:149], v[178:181], v[124:127]
	v_mfma_f32_16x16x32_bf16 v[124:127], v[150:153], v[182:185], v[124:127]
	v_mfma_f32_16x16x32_bf16 v[108:111], v[150:153], v[190:193], v[108:111]
	v_mfma_f32_16x16x32_bf16 v[108:111], v[146:149], v[186:189], v[108:111]
	v_mfma_f32_16x16x32_bf16 v[92:95], v[146:149], v[194:197], v[92:95]
	v_mfma_f32_16x16x32_bf16 v[92:95], v[150:153], v[198:201], v[92:95]
	v_mfma_f32_16x16x32_bf16 v[76:79], v[150:153], v[206:209], v[76:79]
	v_mfma_f32_16x16x32_bf16 v[76:79], v[146:149], v[202:205], v[76:79]
	v_mfma_f32_16x16x32_bf16 v[64:67], v[154:157], v[202:205], v[64:67]
	v_mfma_f32_16x16x32_bf16 v[64:67], v[158:161], v[206:209], v[64:67]
	v_mfma_f32_16x16x32_bf16 v[80:83], v[158:161], v[198:201], v[80:83]
	v_mfma_f32_16x16x32_bf16 v[80:83], v[154:157], v[194:197], v[80:83]
	v_mfma_f32_16x16x32_bf16 v[96:99], v[154:157], v[186:189], v[96:99]
	v_mfma_f32_16x16x32_bf16 v[96:99], v[158:161], v[190:193], v[96:99]
	v_mfma_f32_16x16x32_bf16 v[112:115], v[158:161], v[182:185], v[112:115]
	v_mfma_f32_16x16x32_bf16 v[112:115], v[154:157], v[178:181], v[112:115]
	v_mfma_f32_16x16x32_bf16 v[120:123], v[162:165], v[178:181], v[120:123]
	v_mfma_f32_16x16x32_bf16 v[120:123], v[166:169], v[182:185], v[120:123]
	v_mfma_f32_16x16x32_bf16 v[104:107], v[166:169], v[190:193], v[104:107]
	v_mfma_f32_16x16x32_bf16 v[104:107], v[162:165], v[186:189], v[104:107]
	v_mfma_f32_16x16x32_bf16 v[88:91], v[162:165], v[194:197], v[88:91]
	v_mfma_f32_16x16x32_bf16 v[88:91], v[166:169], v[198:201], v[88:91]
	v_mfma_f32_16x16x32_bf16 v[72:75], v[166:169], v[206:209], v[72:75]
	v_mfma_f32_16x16x32_bf16 v[72:75], v[162:165], v[202:205], v[72:75]
	v_mfma_f32_16x16x32_bf16 v[68:71], v[170:173], v[202:205], v[68:71]
	v_mfma_f32_16x16x32_bf16 v[68:71], v[174:177], v[206:209], v[68:71]
	v_mfma_f32_16x16x32_bf16 v[84:87], v[174:177], v[198:201], v[84:87]
	v_mfma_f32_16x16x32_bf16 v[84:87], v[170:173], v[194:197], v[84:87]
	v_mfma_f32_16x16x32_bf16 v[100:103], v[170:173], v[186:189], v[100:103]
	v_mfma_f32_16x16x32_bf16 v[100:103], v[174:177], v[190:193], v[100:103]
	v_mfma_f32_16x16x32_bf16 v[116:119], v[174:177], v[182:185], v[116:119]
	v_mfma_f32_16x16x32_bf16 v[116:119], v[170:173], v[178:181], v[116:119]
	s_barrier
	s_mov_b32 m0, s68
	v_lshl_add_u64 v[212:213], s[84:85], 0, v[128:129]
	global_load_lds_dwordx4 v[212:213], off
	v_lshl_add_u64 v[214:215], v[212:213], 0, s[0:1]
	s_mov_b32 m0, s69
	s_nop 0
	global_load_lds_dwordx4 v[214:215], off
	v_lshl_add_u64 v[214:215], v[212:213], 0, s[2:3]
	s_mov_b32 m0, s70
	s_nop 0
	global_load_lds_dwordx4 v[214:215], off
	v_lshl_add_u64 v[214:215], v[212:213], 0, s[8:9]
	s_mov_b32 m0, s71
	s_nop 0
	global_load_lds_dwordx4 v[214:215], off
	v_lshl_add_u64 v[214:215], s[44:45], 0, v[130:131]
	s_mov_b32 m0, s39
	v_lshl_add_u64 v[216:217], v[214:215], 0, s[0:1]
	global_load_lds_dwordx4 v[214:215], off
	s_mov_b32 m0, s56
	s_nop 0
	global_load_lds_dwordx4 v[216:217], off
	ds_read_b128 v[178:181], v143 offset:16384
	ds_read_b128 v[182:185], v143 offset:17408
	ds_read_b128 v[186:189], v143 offset:18432
	ds_read_b128 v[190:193], v143 offset:19456
	ds_read_b128 v[194:197], v143 offset:20480
	ds_read_b128 v[198:201], v143 offset:21504
	ds_read_b128 v[202:205], v143 offset:22528
	ds_read_b128 v[206:209], v143 offset:23552
	s_waitcnt vmcnt(8)
	s_waitcnt lgkmcnt(0)
	s_barrier
	s_waitcnt lgkmcnt(0)
	v_mfma_f32_16x16x32_bf16 v[60:63], v[146:149], v[178:181], v[60:63]
	v_mfma_f32_16x16x32_bf16 v[60:63], v[150:153], v[182:185], v[60:63]
	v_mfma_f32_16x16x32_bf16 v[44:47], v[150:153], v[190:193], v[44:47]
	v_mfma_f32_16x16x32_bf16 v[44:47], v[146:149], v[186:189], v[44:47]
	v_mfma_f32_16x16x32_bf16 v[28:31], v[146:149], v[194:197], v[28:31]
	v_mfma_f32_16x16x32_bf16 v[28:31], v[150:153], v[198:201], v[28:31]
	v_mfma_f32_16x16x32_bf16 v[12:15], v[150:153], v[206:209], v[12:15]
	v_mfma_f32_16x16x32_bf16 v[12:15], v[146:149], v[202:205], v[12:15]
	v_mfma_f32_16x16x32_bf16 v[0:3], v[154:157], v[202:205], v[0:3]
	v_mfma_f32_16x16x32_bf16 v[0:3], v[158:161], v[206:209], v[0:3]
	v_mfma_f32_16x16x32_bf16 v[16:19], v[158:161], v[198:201], v[16:19]
	v_mfma_f32_16x16x32_bf16 v[16:19], v[154:157], v[194:197], v[16:19]
	v_mfma_f32_16x16x32_bf16 v[32:35], v[154:157], v[186:189], v[32:35]
	v_mfma_f32_16x16x32_bf16 v[32:35], v[158:161], v[190:193], v[32:35]
	v_mfma_f32_16x16x32_bf16 v[48:51], v[158:161], v[182:185], v[48:51]
	v_mfma_f32_16x16x32_bf16 v[48:51], v[154:157], v[178:181], v[48:51]
	v_mfma_f32_16x16x32_bf16 v[56:59], v[162:165], v[178:181], v[56:59]
	v_mfma_f32_16x16x32_bf16 v[56:59], v[166:169], v[182:185], v[56:59]
	v_mfma_f32_16x16x32_bf16 v[40:43], v[166:169], v[190:193], v[40:43]
	v_mfma_f32_16x16x32_bf16 v[40:43], v[162:165], v[186:189], v[40:43]
	v_mfma_f32_16x16x32_bf16 v[24:27], v[162:165], v[194:197], v[24:27]
	v_mfma_f32_16x16x32_bf16 v[24:27], v[166:169], v[198:201], v[24:27]
	v_mfma_f32_16x16x32_bf16 v[8:11], v[166:169], v[206:209], v[8:11]
	v_mfma_f32_16x16x32_bf16 v[8:11], v[162:165], v[202:205], v[8:11]
	v_mfma_f32_16x16x32_bf16 v[4:7], v[170:173], v[202:205], v[4:7]
	v_mfma_f32_16x16x32_bf16 v[4:7], v[174:177], v[206:209], v[4:7]
	v_mfma_f32_16x16x32_bf16 v[20:23], v[174:177], v[198:201], v[20:23]
	v_mfma_f32_16x16x32_bf16 v[20:23], v[170:173], v[194:197], v[20:23]
	v_mfma_f32_16x16x32_bf16 v[36:39], v[170:173], v[186:189], v[36:39]
	v_mfma_f32_16x16x32_bf16 v[36:39], v[174:177], v[190:193], v[36:39]
	v_mfma_f32_16x16x32_bf16 v[52:55], v[174:177], v[182:185], v[52:55]
	v_mfma_f32_16x16x32_bf16 v[52:55], v[170:173], v[178:181], v[52:55]
	s_barrier
	s_mov_b32 m0, s57
	v_lshl_add_u64 v[216:217], v[214:215], 0, s[2:3]
	global_load_lds_dwordx4 v[216:217], off
	v_lshl_add_u64 v[216:217], v[214:215], 0, s[8:9]
	s_mov_b32 m0, s58
	s_nop 0
	global_load_lds_dwordx4 v[216:217], off
	ds_read_b128 v[146:149], v144
	ds_read_b128 v[150:153], v144 offset:1024
	ds_read_b128 v[154:157], v144 offset:2048
	ds_read_b128 v[158:161], v144 offset:3072
	ds_read_b128 v[162:165], v136
	ds_read_b128 v[166:169], v136 offset:1024
	ds_read_b128 v[170:173], v136 offset:2048
	ds_read_b128 v[174:177], v136 offset:3072
	ds_read_b128 v[178:181], v143 offset:32768
	ds_read_b128 v[182:185], v143 offset:33792
	ds_read_b128 v[186:189], v143 offset:34816
	ds_read_b128 v[190:193], v143 offset:35840
	ds_read_b128 v[194:197], v143 offset:36864
	ds_read_b128 v[198:201], v143 offset:37888
	ds_read_b128 v[202:205], v143 offset:38912
	ds_read_b128 v[206:209], v143 offset:39936
	s_waitcnt vmcnt(8)
	s_waitcnt lgkmcnt(0)
	s_barrier
	s_waitcnt lgkmcnt(0)
	v_mfma_f32_16x16x32_bf16 v[124:127], v[146:149], v[178:181], v[124:127]
	v_mfma_f32_16x16x32_bf16 v[124:127], v[150:153], v[182:185], v[124:127]
	v_mfma_f32_16x16x32_bf16 v[108:111], v[150:153], v[190:193], v[108:111]
	v_mfma_f32_16x16x32_bf16 v[108:111], v[146:149], v[186:189], v[108:111]
	v_mfma_f32_16x16x32_bf16 v[92:95], v[146:149], v[194:197], v[92:95]
	v_mfma_f32_16x16x32_bf16 v[92:95], v[150:153], v[198:201], v[92:95]
	v_mfma_f32_16x16x32_bf16 v[76:79], v[150:153], v[206:209], v[76:79]
	v_mfma_f32_16x16x32_bf16 v[76:79], v[146:149], v[202:205], v[76:79]
	v_mfma_f32_16x16x32_bf16 v[64:67], v[154:157], v[202:205], v[64:67]
	v_mfma_f32_16x16x32_bf16 v[64:67], v[158:161], v[206:209], v[64:67]
	v_mfma_f32_16x16x32_bf16 v[80:83], v[158:161], v[198:201], v[80:83]
	v_mfma_f32_16x16x32_bf16 v[80:83], v[154:157], v[194:197], v[80:83]
	v_mfma_f32_16x16x32_bf16 v[96:99], v[154:157], v[186:189], v[96:99]
	v_mfma_f32_16x16x32_bf16 v[96:99], v[158:161], v[190:193], v[96:99]
	v_mfma_f32_16x16x32_bf16 v[112:115], v[158:161], v[182:185], v[112:115]
	v_mfma_f32_16x16x32_bf16 v[112:115], v[154:157], v[178:181], v[112:115]
	v_mfma_f32_16x16x32_bf16 v[120:123], v[162:165], v[178:181], v[120:123]
	v_mfma_f32_16x16x32_bf16 v[120:123], v[166:169], v[182:185], v[120:123]
	v_mfma_f32_16x16x32_bf16 v[104:107], v[166:169], v[190:193], v[104:107]
	v_mfma_f32_16x16x32_bf16 v[104:107], v[162:165], v[186:189], v[104:107]
	v_mfma_f32_16x16x32_bf16 v[88:91], v[162:165], v[194:197], v[88:91]
	v_mfma_f32_16x16x32_bf16 v[88:91], v[166:169], v[198:201], v[88:91]
	v_mfma_f32_16x16x32_bf16 v[72:75], v[166:169], v[206:209], v[72:75]
	v_mfma_f32_16x16x32_bf16 v[72:75], v[162:165], v[202:205], v[72:75]
	v_mfma_f32_16x16x32_bf16 v[68:71], v[170:173], v[202:205], v[68:71]
	v_mfma_f32_16x16x32_bf16 v[68:71], v[174:177], v[206:209], v[68:71]
	v_mfma_f32_16x16x32_bf16 v[84:87], v[174:177], v[198:201], v[84:87]
	v_mfma_f32_16x16x32_bf16 v[84:87], v[170:173], v[194:197], v[84:87]
	v_mfma_f32_16x16x32_bf16 v[100:103], v[170:173], v[186:189], v[100:103]
	v_mfma_f32_16x16x32_bf16 v[100:103], v[174:177], v[190:193], v[100:103]
	v_mfma_f32_16x16x32_bf16 v[116:119], v[174:177], v[182:185], v[116:119]
	v_mfma_f32_16x16x32_bf16 v[116:119], v[170:173], v[178:181], v[116:119]
	s_barrier
	s_mov_b32 m0, s77
	v_lshl_add_u64 v[216:217], v[212:213], 0, s[18:19]
	global_load_lds_dwordx4 v[216:217], off
	v_lshl_add_u64 v[216:217], v[212:213], 0, s[20:21]
	s_mov_b32 m0, s78
	s_nop 0
	global_load_lds_dwordx4 v[216:217], off
	v_lshl_add_u64 v[216:217], v[212:213], 0, s[22:23]
	s_mov_b32 m0, s79
	v_lshl_add_u64 v[212:213], v[212:213], 0, s[24:25]
	global_load_lds_dwordx4 v[216:217], off
	s_mov_b32 m0, s80
	s_nop 0
	global_load_lds_dwordx4 v[212:213], off
	v_lshl_add_u64 v[212:213], v[214:215], 0, s[18:19]
	s_mov_b32 m0, s60
	s_nop 0
	global_load_lds_dwordx4 v[212:213], off
	v_lshl_add_u64 v[212:213], v[214:215], 0, s[20:21]
	s_mov_b32 m0, s61
	s_nop 0
	global_load_lds_dwordx4 v[212:213], off
	ds_read_b128 v[178:181], v143 offset:49152
	ds_read_b128 v[182:185], v143 offset:50176
	ds_read_b128 v[186:189], v143 offset:51200
	ds_read_b128 v[190:193], v143 offset:52224
	ds_read_b128 v[194:197], v143 offset:53248
	ds_read_b128 v[198:201], v143 offset:54272
	ds_read_b128 v[202:205], v143 offset:55296
	ds_read_b128 v[206:209], v143 offset:56320
	s_waitcnt vmcnt(8)
	s_waitcnt lgkmcnt(0)
	s_barrier
	s_waitcnt lgkmcnt(0)
	v_mfma_f32_16x16x32_bf16 v[60:63], v[146:149], v[178:181], v[60:63]
	v_mfma_f32_16x16x32_bf16 v[60:63], v[150:153], v[182:185], v[60:63]
	v_mfma_f32_16x16x32_bf16 v[44:47], v[150:153], v[190:193], v[44:47]
	v_mfma_f32_16x16x32_bf16 v[44:47], v[146:149], v[186:189], v[44:47]
	v_mfma_f32_16x16x32_bf16 v[28:31], v[146:149], v[194:197], v[28:31]
	v_mfma_f32_16x16x32_bf16 v[28:31], v[150:153], v[198:201], v[28:31]
	v_mfma_f32_16x16x32_bf16 v[12:15], v[150:153], v[206:209], v[12:15]
	v_mfma_f32_16x16x32_bf16 v[12:15], v[146:149], v[202:205], v[12:15]
	v_mfma_f32_16x16x32_bf16 v[0:3], v[154:157], v[202:205], v[0:3]
	v_mfma_f32_16x16x32_bf16 v[0:3], v[158:161], v[206:209], v[0:3]
	v_mfma_f32_16x16x32_bf16 v[16:19], v[158:161], v[198:201], v[16:19]
	v_mfma_f32_16x16x32_bf16 v[16:19], v[154:157], v[194:197], v[16:19]
	v_mfma_f32_16x16x32_bf16 v[32:35], v[154:157], v[186:189], v[32:35]
	v_mfma_f32_16x16x32_bf16 v[32:35], v[158:161], v[190:193], v[32:35]
	v_mfma_f32_16x16x32_bf16 v[48:51], v[158:161], v[182:185], v[48:51]
	v_mfma_f32_16x16x32_bf16 v[48:51], v[154:157], v[178:181], v[48:51]
	v_mfma_f32_16x16x32_bf16 v[56:59], v[162:165], v[178:181], v[56:59]
	v_mfma_f32_16x16x32_bf16 v[56:59], v[166:169], v[182:185], v[56:59]
	v_mfma_f32_16x16x32_bf16 v[40:43], v[166:169], v[190:193], v[40:43]
	v_mfma_f32_16x16x32_bf16 v[40:43], v[162:165], v[186:189], v[40:43]
	v_mfma_f32_16x16x32_bf16 v[24:27], v[162:165], v[194:197], v[24:27]
	v_mfma_f32_16x16x32_bf16 v[24:27], v[166:169], v[198:201], v[24:27]
	v_mfma_f32_16x16x32_bf16 v[8:11], v[166:169], v[206:209], v[8:11]
	v_mfma_f32_16x16x32_bf16 v[8:11], v[162:165], v[202:205], v[8:11]
	v_mfma_f32_16x16x32_bf16 v[4:7], v[170:173], v[202:205], v[4:7]
	v_mfma_f32_16x16x32_bf16 v[4:7], v[174:177], v[206:209], v[4:7]
	v_mfma_f32_16x16x32_bf16 v[20:23], v[174:177], v[198:201], v[20:23]
	v_mfma_f32_16x16x32_bf16 v[20:23], v[170:173], v[194:197], v[20:23]
	v_mfma_f32_16x16x32_bf16 v[36:39], v[170:173], v[186:189], v[36:39]
	v_mfma_f32_16x16x32_bf16 v[36:39], v[174:177], v[190:193], v[36:39]
	v_mfma_f32_16x16x32_bf16 v[52:55], v[174:177], v[182:185], v[52:55]
	v_mfma_f32_16x16x32_bf16 v[52:55], v[170:173], v[178:181], v[52:55]
	s_barrier
	s_cmp_gt_u32 s29, 13
	s_cbranch_scc0 .LBB0_175
	s_and_b64 vcc, exec, s[26:27]
	s_cbranch_vccz .LBB0_178
	s_barrier

.LBB0_255:
	s_add_i32 s73, s73, 2
	s_mov_b32 s74, s73
	s_ashr_i32 s75, s74, 31
	s_lshl_b64 s[76:77], s[74:75], 7
	s_add_u32 s75, s76, 0x100
	s_addc_u32 s78, s77, 0
	s_add_u32 s79, s40, s75
	s_addc_u32 s80, s41, s78
	s_add_u32 s81, s38, s75
	s_addc_u32 s78, s39, s78
	s_cmp_eq_u32 s74, 42
	s_cselect_b32 s75, s1, s80
	s_cselect_b32 s74, s0, s79
	s_cselect_b32 s79, s43, s78
	s_cselect_b32 s78, s42, s81
	v_lshl_add_u64 v[208:209], v[136:137], 0, s[76:77]
	v_lshl_add_u64 v[212:213], v[208:209], 0, s[20:21]
	s_add_i32 m0, s53, 0xc000
	s_nop 0
	global_load_lds_dwordx4 v[212:213], off
	v_lshl_add_u64 v[208:209], v[208:209], 0, s[22:23]
	s_add_i32 m0, s53, 0xe000
	s_nop 0
	global_load_lds_dwordx4 v[208:209], off
	ds_read_b128 v[144:147], v141
	ds_read_b128 v[148:151], v141 offset:1024
	ds_read_b128 v[152:155], v141 offset:2048
	ds_read_b128 v[156:159], v141 offset:3072
	ds_read_b128 v[160:163], v142
	ds_read_b128 v[164:167], v142 offset:1024
	ds_read_b128 v[168:171], v142 offset:2048
	ds_read_b128 v[172:175], v142 offset:3072
	ds_read_b128 v[176:179], v143
	ds_read_b128 v[180:183], v143 offset:1024
	ds_read_b128 v[184:187], v143 offset:2048
	ds_read_b128 v[188:191], v143 offset:3072
	ds_read_b128 v[192:195], v143 offset:4096
	ds_read_b128 v[196:199], v143 offset:5120
	ds_read_b128 v[200:203], v143 offset:6144
	ds_read_b128 v[204:207], v143 offset:7168
	s_waitcnt vmcnt(8)
	s_waitcnt lgkmcnt(0)
	s_barrier
	s_waitcnt lgkmcnt(0)
	v_mfma_f32_16x16x32_bf16 v[124:127], v[144:147], v[176:179], v[124:127]
	v_mfma_f32_16x16x32_bf16 v[124:127], v[148:151], v[180:183], v[124:127]
	v_mfma_f32_16x16x32_bf16 v[116:119], v[148:151], v[188:191], v[116:119]
	v_mfma_f32_16x16x32_bf16 v[116:119], v[144:147], v[184:187], v[116:119]
	v_mfma_f32_16x16x32_bf16 v[100:103], v[144:147], v[192:195], v[100:103]
	v_mfma_f32_16x16x32_bf16 v[100:103], v[148:151], v[196:199], v[100:103]
	v_mfma_f32_16x16x32_bf16 v[84:87], v[148:151], v[204:207], v[84:87]
	v_mfma_f32_16x16x32_bf16 v[84:87], v[144:147], v[200:203], v[84:87]
	v_mfma_f32_16x16x32_bf16 v[80:83], v[152:155], v[200:203], v[80:83]
	v_mfma_f32_16x16x32_bf16 v[80:83], v[156:159], v[204:207], v[80:83]
	v_mfma_f32_16x16x32_bf16 v[96:99], v[156:159], v[196:199], v[96:99]
	v_mfma_f32_16x16x32_bf16 v[96:99], v[152:155], v[192:195], v[96:99]
	v_mfma_f32_16x16x32_bf16 v[112:115], v[152:155], v[184:187], v[112:115]
	v_mfma_f32_16x16x32_bf16 v[112:115], v[156:159], v[188:191], v[112:115]
	v_mfma_f32_16x16x32_bf16 v[120:123], v[156:159], v[180:183], v[120:123]
	v_mfma_f32_16x16x32_bf16 v[120:123], v[152:155], v[176:179], v[120:123]
	v_mfma_f32_16x16x32_bf16 v[108:111], v[160:163], v[176:179], v[108:111]
	v_mfma_f32_16x16x32_bf16 v[108:111], v[164:167], v[180:183], v[108:111]
	v_mfma_f32_16x16x32_bf16 v[92:95], v[164:167], v[188:191], v[92:95]
	v_mfma_f32_16x16x32_bf16 v[92:95], v[160:163], v[184:187], v[92:95]
	v_mfma_f32_16x16x32_bf16 v[76:79], v[160:163], v[192:195], v[76:79]
	v_mfma_f32_16x16x32_bf16 v[76:79], v[164:167], v[196:199], v[76:79]
	v_mfma_f32_16x16x32_bf16 v[68:71], v[164:167], v[204:207], v[68:71]
	v_mfma_f32_16x16x32_bf16 v[68:71], v[160:163], v[200:203], v[68:71]
	v_mfma_f32_16x16x32_bf16 v[64:67], v[168:171], v[200:203], v[64:67]
	v_mfma_f32_16x16x32_bf16 v[64:67], v[172:175], v[204:207], v[64:67]
	v_mfma_f32_16x16x32_bf16 v[72:75], v[172:175], v[196:199], v[72:75]
	v_mfma_f32_16x16x32_bf16 v[72:75], v[168:171], v[192:195], v[72:75]
	v_mfma_f32_16x16x32_bf16 v[88:91], v[168:171], v[184:187], v[88:91]
	v_mfma_f32_16x16x32_bf16 v[88:91], v[172:175], v[188:191], v[88:91]
	v_mfma_f32_16x16x32_bf16 v[104:107], v[172:175], v[180:183], v[104:107]
	v_mfma_f32_16x16x32_bf16 v[104:107], v[168:171], v[176:179], v[104:107]
	s_barrier
	s_add_i32 s76, s63, s52
	v_lshl_add_u64 v[208:209], s[78:79], 0, v[130:131]
	s_mov_b32 m0, s76
	s_nop 0
	global_load_lds_dwordx4 v[208:209], off
	v_lshl_add_u64 v[212:213], v[208:209], 0, s[2:3]
	s_add_i32 m0, s76, 0x2000
	s_add_i32 s76, s64, s52
	global_load_lds_dwordx4 v[212:213], off
	v_lshl_add_u64 v[212:213], v[208:209], 0, s[8:9]
	s_mov_b32 m0, s76
	s_nop 0
	global_load_lds_dwordx4 v[212:213], off
	v_lshl_add_u64 v[212:213], v[208:209], 0, s[14:15]
	s_add_i32 m0, s76, 0x2000
	s_nop 0
	global_load_lds_dwordx4 v[212:213], off
	v_lshl_add_u64 v[212:213], s[74:75], 0, v[128:129]
	s_mov_b32 m0, s53
	v_lshl_add_u64 v[214:215], v[212:213], 0, s[2:3]
	global_load_lds_dwordx4 v[212:213], off
	s_mov_b32 m0, s54
	s_nop 0
	global_load_lds_dwordx4 v[214:215], off
	ds_read_b128 v[176:179], v143 offset:16384
	ds_read_b128 v[180:183], v143 offset:17408
	ds_read_b128 v[184:187], v143 offset:18432
	ds_read_b128 v[188:191], v143 offset:19456
	ds_read_b128 v[192:195], v143 offset:20480
	ds_read_b128 v[196:199], v143 offset:21504
	ds_read_b128 v[200:203], v143 offset:22528
	ds_read_b128 v[204:207], v143 offset:23552
	s_waitcnt vmcnt(8)
	s_waitcnt lgkmcnt(0)
	s_barrier
	s_waitcnt lgkmcnt(0)
	v_mfma_f32_16x16x32_bf16 v[60:63], v[144:147], v[176:179], v[60:63]
	v_mfma_f32_16x16x32_bf16 v[60:63], v[148:151], v[180:183], v[60:63]
	v_mfma_f32_16x16x32_bf16 v[52:55], v[148:151], v[188:191], v[52:55]
	v_mfma_f32_16x16x32_bf16 v[52:55], v[144:147], v[184:187], v[52:55]
	v_mfma_f32_16x16x32_bf16 v[36:39], v[144:147], v[192:195], v[36:39]
	v_mfma_f32_16x16x32_bf16 v[36:39], v[148:151], v[196:199], v[36:39]
	v_mfma_f32_16x16x32_bf16 v[20:23], v[148:151], v[204:207], v[20:23]
	v_mfma_f32_16x16x32_bf16 v[20:23], v[144:147], v[200:203], v[20:23]
	v_mfma_f32_16x16x32_bf16 v[16:19], v[152:155], v[200:203], v[16:19]
	v_mfma_f32_16x16x32_bf16 v[16:19], v[156:159], v[204:207], v[16:19]
	v_mfma_f32_16x16x32_bf16 v[32:35], v[156:159], v[196:199], v[32:35]
	v_mfma_f32_16x16x32_bf16 v[32:35], v[152:155], v[192:195], v[32:35]
	v_mfma_f32_16x16x32_bf16 v[48:51], v[152:155], v[184:187], v[48:51]
	v_mfma_f32_16x16x32_bf16 v[48:51], v[156:159], v[188:191], v[48:51]
	v_mfma_f32_16x16x32_bf16 v[56:59], v[156:159], v[180:183], v[56:59]
	v_mfma_f32_16x16x32_bf16 v[56:59], v[152:155], v[176:179], v[56:59]
	v_mfma_f32_16x16x32_bf16 v[44:47], v[160:163], v[176:179], v[44:47]
	v_mfma_f32_16x16x32_bf16 v[44:47], v[164:167], v[180:183], v[44:47]
	v_mfma_f32_16x16x32_bf16 v[28:31], v[164:167], v[188:191], v[28:31]
	v_mfma_f32_16x16x32_bf16 v[28:31], v[160:163], v[184:187], v[28:31]
	v_mfma_f32_16x16x32_bf16 v[12:15], v[160:163], v[192:195], v[12:15]
	v_mfma_f32_16x16x32_bf16 v[12:15], v[164:167], v[196:199], v[12:15]
	v_mfma_f32_16x16x32_bf16 v[4:7], v[164:167], v[204:207], v[4:7]
	v_mfma_f32_16x16x32_bf16 v[4:7], v[160:163], v[200:203], v[4:7]
	v_mfma_f32_16x16x32_bf16 v[0:3], v[168:171], v[200:203], v[0:3]
	v_mfma_f32_16x16x32_bf16 v[0:3], v[172:175], v[204:207], v[0:3]
	v_mfma_f32_16x16x32_bf16 v[8:11], v[172:175], v[196:199], v[8:11]
	v_mfma_f32_16x16x32_bf16 v[8:11], v[168:171], v[192:195], v[8:11]
	v_mfma_f32_16x16x32_bf16 v[24:27], v[168:171], v[184:187], v[24:27]
	v_mfma_f32_16x16x32_bf16 v[24:27], v[172:175], v[188:191], v[24:27]
	v_mfma_f32_16x16x32_bf16 v[40:43], v[172:175], v[180:183], v[40:43]
	v_mfma_f32_16x16x32_bf16 v[40:43], v[168:171], v[176:179], v[40:43]
	s_barrier
	s_add_i32 s74, 0, 0x18000
	s_add_i32 s75, 0, 0x1c000
	v_add_u32_e32 v156, s74, v140
	v_add_u32_e32 v172, s75, v140
	s_mov_b32 m0, s55
	v_lshl_add_u64 v[214:215], v[212:213], 0, s[8:9]
	global_load_lds_dwordx4 v[214:215], off
	v_lshl_add_u64 v[214:215], v[212:213], 0, s[14:15]
	s_mov_b32 m0, s56
	s_nop 0
	global_load_lds_dwordx4 v[214:215], off
	ds_read_b128 v[144:147], v156
	ds_read_b128 v[148:151], v156 offset:1024
	ds_read_b128 v[152:155], v156 offset:2048
	ds_read_b128 v[156:159], v156 offset:3072
	ds_read_b128 v[160:163], v172
	ds_read_b128 v[164:167], v172 offset:1024
	ds_read_b128 v[168:171], v172 offset:2048
	ds_read_b128 v[172:175], v172 offset:3072
	ds_read_b128 v[176:179], v143 offset:32768
	ds_read_b128 v[180:183], v143 offset:33792
	ds_read_b128 v[184:187], v143 offset:34816
	ds_read_b128 v[188:191], v143 offset:35840
	ds_read_b128 v[192:195], v143 offset:36864
	ds_read_b128 v[196:199], v143 offset:37888
	ds_read_b128 v[200:203], v143 offset:38912
	ds_read_b128 v[204:207], v143 offset:39936
	s_waitcnt vmcnt(8)
	s_waitcnt lgkmcnt(0)
	s_barrier
	s_waitcnt lgkmcnt(0)
	v_mfma_f32_16x16x32_bf16 v[124:127], v[144:147], v[176:179], v[124:127]
	v_mfma_f32_16x16x32_bf16 v[124:127], v[148:151], v[180:183], v[124:127]
	v_mfma_f32_16x16x32_bf16 v[116:119], v[148:151], v[188:191], v[116:119]
	v_mfma_f32_16x16x32_bf16 v[116:119], v[144:147], v[184:187], v[116:119]
	v_mfma_f32_16x16x32_bf16 v[100:103], v[144:147], v[192:195], v[100:103]
	v_mfma_f32_16x16x32_bf16 v[100:103], v[148:151], v[196:199], v[100:103]
	v_mfma_f32_16x16x32_bf16 v[84:87], v[148:151], v[204:207], v[84:87]
	v_mfma_f32_16x16x32_bf16 v[84:87], v[144:147], v[200:203], v[84:87]
	v_mfma_f32_16x16x32_bf16 v[80:83], v[152:155], v[200:203], v[80:83]
	v_mfma_f32_16x16x32_bf16 v[80:83], v[156:159], v[204:207], v[80:83]
	v_mfma_f32_16x16x32_bf16 v[96:99], v[156:159], v[196:199], v[96:99]
	v_mfma_f32_16x16x32_bf16 v[96:99], v[152:155], v[192:195], v[96:99]
	v_mfma_f32_16x16x32_bf16 v[112:115], v[152:155], v[184:187], v[112:115]
	v_mfma_f32_16x16x32_bf16 v[112:115], v[156:159], v[188:191], v[112:115]
	v_mfma_f32_16x16x32_bf16 v[120:123], v[156:159], v[180:183], v[120:123]
	v_mfma_f32_16x16x32_bf16 v[120:123], v[152:155], v[176:179], v[120:123]
	v_mfma_f32_16x16x32_bf16 v[108:111], v[160:163], v[176:179], v[108:111]
	v_mfma_f32_16x16x32_bf16 v[108:111], v[164:167], v[180:183], v[108:111]
	v_mfma_f32_16x16x32_bf16 v[92:95], v[164:167], v[188:191], v[92:95]
	v_mfma_f32_16x16x32_bf16 v[92:95], v[160:163], v[184:187], v[92:95]
	v_mfma_f32_16x16x32_bf16 v[76:79], v[160:163], v[192:195], v[76:79]
	v_mfma_f32_16x16x32_bf16 v[76:79], v[164:167], v[196:199], v[76:79]
	v_mfma_f32_16x16x32_bf16 v[68:71], v[164:167], v[204:207], v[68:71]
	v_mfma_f32_16x16x32_bf16 v[68:71], v[160:163], v[200:203], v[68:71]
	v_mfma_f32_16x16x32_bf16 v[64:67], v[168:171], v[200:203], v[64:67]
	v_mfma_f32_16x16x32_bf16 v[64:67], v[172:175], v[204:207], v[64:67]
	v_mfma_f32_16x16x32_bf16 v[72:75], v[172:175], v[196:199], v[72:75]
	v_mfma_f32_16x16x32_bf16 v[72:75], v[168:171], v[192:195], v[72:75]
	v_mfma_f32_16x16x32_bf16 v[88:91], v[168:171], v[184:187], v[88:91]
	v_mfma_f32_16x16x32_bf16 v[88:91], v[172:175], v[188:191], v[88:91]
	v_mfma_f32_16x16x32_bf16 v[104:107], v[172:175], v[180:183], v[104:107]
	v_mfma_f32_16x16x32_bf16 v[104:107], v[168:171], v[176:179], v[104:107]
	s_barrier
	s_add_i32 s74, s74, s52
	v_lshl_add_u64 v[214:215], v[208:209], 0, s[20:21]
	s_mov_b32 m0, s74
	s_nop 0
	global_load_lds_dwordx4 v[214:215], off
	v_lshl_add_u64 v[214:215], v[208:209], 0, s[22:23]
	s_add_i32 m0, s74, 0x2000
	s_add_i32 s74, s75, s52
	global_load_lds_dwordx4 v[214:215], off
	v_lshl_add_u64 v[214:215], v[208:209], 0, s[24:25]
	s_mov_b32 m0, s74
	v_lshl_add_u64 v[208:209], v[208:209], 0, s[26:27]
	global_load_lds_dwordx4 v[214:215], off
	s_add_i32 m0, s74, 0x2000
	s_nop 0
	global_load_lds_dwordx4 v[208:209], off
	v_lshl_add_u64 v[208:209], v[212:213], 0, s[20:21]
	s_mov_b32 m0, s58
	s_nop 0
	global_load_lds_dwordx4 v[208:209], off
	v_lshl_add_u64 v[208:209], v[212:213], 0, s[22:23]
	s_mov_b32 m0, s59
	s_nop 0
	global_load_lds_dwordx4 v[208:209], off
	ds_read_b128 v[176:179], v143 offset:49152
	ds_read_b128 v[180:183], v143 offset:50176
	ds_read_b128 v[184:187], v143 offset:51200
	ds_read_b128 v[188:191], v143 offset:52224
	ds_read_b128 v[192:195], v143 offset:53248
	ds_read_b128 v[196:199], v143 offset:54272
	ds_read_b128 v[200:203], v143 offset:55296
	ds_read_b128 v[204:207], v143 offset:56320
	s_waitcnt vmcnt(8)
	s_waitcnt lgkmcnt(0)
	s_barrier
	s_waitcnt lgkmcnt(0)
	v_mfma_f32_16x16x32_bf16 v[60:63], v[144:147], v[176:179], v[60:63]
	v_mfma_f32_16x16x32_bf16 v[60:63], v[148:151], v[180:183], v[60:63]
	v_mfma_f32_16x16x32_bf16 v[52:55], v[148:151], v[188:191], v[52:55]
	v_mfma_f32_16x16x32_bf16 v[52:55], v[144:147], v[184:187], v[52:55]
	v_mfma_f32_16x16x32_bf16 v[36:39], v[144:147], v[192:195], v[36:39]
	v_mfma_f32_16x16x32_bf16 v[36:39], v[148:151], v[196:199], v[36:39]
	v_mfma_f32_16x16x32_bf16 v[20:23], v[148:151], v[204:207], v[20:23]
	v_mfma_f32_16x16x32_bf16 v[20:23], v[144:147], v[200:203], v[20:23]
	v_mfma_f32_16x16x32_bf16 v[16:19], v[152:155], v[200:203], v[16:19]
	v_mfma_f32_16x16x32_bf16 v[16:19], v[156:159], v[204:207], v[16:19]
	v_mfma_f32_16x16x32_bf16 v[32:35], v[156:159], v[196:199], v[32:35]
	v_mfma_f32_16x16x32_bf16 v[32:35], v[152:155], v[192:195], v[32:35]
	v_mfma_f32_16x16x32_bf16 v[48:51], v[152:155], v[184:187], v[48:51]
	v_mfma_f32_16x16x32_bf16 v[48:51], v[156:159], v[188:191], v[48:51]
	v_mfma_f32_16x16x32_bf16 v[56:59], v[156:159], v[180:183], v[56:59]
	v_mfma_f32_16x16x32_bf16 v[56:59], v[152:155], v[176:179], v[56:59]
	v_mfma_f32_16x16x32_bf16 v[44:47], v[160:163], v[176:179], v[44:47]
	v_mfma_f32_16x16x32_bf16 v[44:47], v[164:167], v[180:183], v[44:47]
	v_mfma_f32_16x16x32_bf16 v[28:31], v[164:167], v[188:191], v[28:31]
	v_mfma_f32_16x16x32_bf16 v[28:31], v[160:163], v[184:187], v[28:31]
	v_mfma_f32_16x16x32_bf16 v[12:15], v[160:163], v[192:195], v[12:15]
	v_mfma_f32_16x16x32_bf16 v[12:15], v[164:167], v[196:199], v[12:15]
	v_mfma_f32_16x16x32_bf16 v[4:7], v[164:167], v[204:207], v[4:7]
	v_mfma_f32_16x16x32_bf16 v[4:7], v[160:163], v[200:203], v[4:7]
	v_mfma_f32_16x16x32_bf16 v[0:3], v[168:171], v[200:203], v[0:3]
	v_mfma_f32_16x16x32_bf16 v[0:3], v[172:175], v[204:207], v[0:3]
	v_mfma_f32_16x16x32_bf16 v[8:11], v[172:175], v[196:199], v[8:11]
	v_mfma_f32_16x16x32_bf16 v[8:11], v[168:171], v[192:195], v[8:11]
	v_mfma_f32_16x16x32_bf16 v[24:27], v[168:171], v[184:187], v[24:27]
	v_mfma_f32_16x16x32_bf16 v[24:27], v[172:175], v[188:191], v[24:27]
	v_mfma_f32_16x16x32_bf16 v[40:43], v[172:175], v[180:183], v[40:43]
	v_mfma_f32_16x16x32_bf16 v[40:43], v[168:171], v[176:179], v[40:43]
	s_barrier
	s_cmp_gt_u32 s73, 41
	s_cbranch_scc0 .LBB0_255
	s_and_b64 vcc, exec, s[28:29]
	s_cbranch_vccz .LBB0_258
	s_barrier

.LBB0_386:
	s_add_i32 s70, s70, 2
	s_mov_b32 s42, s70
	s_ashr_i32 s43, s42, 31
	s_lshl_b64 s[72:73], s[42:43], 7
	s_add_u32 s43, s72, 0x100
	s_addc_u32 s71, s73, 0
	s_add_u32 s79, s8, s43
	s_addc_u32 s80, s9, s71
	s_add_u32 s82, s2, s43
	s_addc_u32 s71, s3, s71
	s_add_i32 s83, 0, 0x10000
	s_cmp_eq_u32 s42, 14
	s_cselect_b32 s43, s1, s80
	s_cselect_b32 s42, s57, s79
	s_cselect_b32 s81, s68, s71
	s_cselect_b32 s80, s69, s82
	s_add_i32 s71, 0, 0x14000
	v_add_u32_e32 v140, s83, v220
	v_add_u32_e32 v156, s71, v220
	s_add_u32 s72, s8, s72
	s_addc_u32 s73, s9, s73
	v_lshl_add_u64 v[222:223], s[72:73], 0, v[182:183]
	v_lshl_add_u64 v[224:225], v[222:223], 0, s[14:15]
	s_add_i32 m0, s39, 0xc000
	s_nop 0
	global_load_lds_dwordx4 v[224:225], off
	v_lshl_add_u64 v[222:223], v[222:223], 0, s[16:17]
	s_add_i32 m0, s39, 0xe000
	s_nop 0
	global_load_lds_dwordx4 v[222:223], off
	ds_read_b128 v[128:131], v140
	ds_read_b128 v[132:135], v140 offset:1024
	ds_read_b128 v[136:139], v140 offset:2048
	ds_read_b128 v[140:143], v140 offset:3072
	ds_read_b128 v[144:147], v156
	ds_read_b128 v[148:151], v156 offset:1024
	ds_read_b128 v[152:155], v156 offset:2048
	ds_read_b128 v[156:159], v156 offset:3072
	ds_read_b128 v[160:163], v221
	ds_read_b128 v[164:167], v221 offset:1024
	ds_read_b128 v[186:189], v221 offset:2048
	ds_read_b128 v[190:193], v221 offset:3072
	ds_read_b128 v[194:197], v221 offset:4096
	ds_read_b128 v[198:201], v221 offset:5120
	ds_read_b128 v[202:205], v221 offset:6144
	ds_read_b128 v[206:209], v221 offset:7168
	s_waitcnt vmcnt(8)
	s_waitcnt lgkmcnt(0)
	s_barrier
	s_waitcnt lgkmcnt(0)
	v_mfma_f32_16x16x32_bf16 v[124:127], v[128:131], v[160:163], v[124:127]
	v_mfma_f32_16x16x32_bf16 v[124:127], v[132:135], v[164:167], v[124:127]
	v_mfma_f32_16x16x32_bf16 v[112:115], v[132:135], v[190:193], v[112:115]
	v_mfma_f32_16x16x32_bf16 v[112:115], v[128:131], v[186:189], v[112:115]
	v_mfma_f32_16x16x32_bf16 v[96:99], v[128:131], v[194:197], v[96:99]
	v_mfma_f32_16x16x32_bf16 v[96:99], v[132:135], v[198:201], v[96:99]
	v_mfma_f32_16x16x32_bf16 v[80:83], v[132:135], v[206:209], v[80:83]
	v_mfma_f32_16x16x32_bf16 v[80:83], v[128:131], v[202:205], v[80:83]
	v_mfma_f32_16x16x32_bf16 v[72:75], v[136:139], v[202:205], v[72:75]
	v_mfma_f32_16x16x32_bf16 v[72:75], v[140:143], v[206:209], v[72:75]
	v_mfma_f32_16x16x32_bf16 v[88:91], v[140:143], v[198:201], v[88:91]
	v_mfma_f32_16x16x32_bf16 v[88:91], v[136:139], v[194:197], v[88:91]
	v_mfma_f32_16x16x32_bf16 v[104:107], v[136:139], v[186:189], v[104:107]
	v_mfma_f32_16x16x32_bf16 v[104:107], v[140:143], v[190:193], v[104:107]
	v_mfma_f32_16x16x32_bf16 v[120:123], v[140:143], v[164:167], v[120:123]
	v_mfma_f32_16x16x32_bf16 v[120:123], v[136:139], v[160:163], v[120:123]
	v_mfma_f32_16x16x32_bf16 v[116:119], v[144:147], v[160:163], v[116:119]
	v_mfma_f32_16x16x32_bf16 v[116:119], v[148:151], v[164:167], v[116:119]
	v_mfma_f32_16x16x32_bf16 v[100:103], v[148:151], v[190:193], v[100:103]
	v_mfma_f32_16x16x32_bf16 v[100:103], v[144:147], v[186:189], v[100:103]
	v_mfma_f32_16x16x32_bf16 v[84:87], v[144:147], v[194:197], v[84:87]
	v_mfma_f32_16x16x32_bf16 v[84:87], v[148:151], v[198:201], v[84:87]
	v_mfma_f32_16x16x32_bf16 v[68:71], v[148:151], v[206:209], v[68:71]
	v_mfma_f32_16x16x32_bf16 v[68:71], v[144:147], v[202:205], v[68:71]
	v_mfma_f32_16x16x32_bf16 v[64:67], v[152:155], v[202:205], v[64:67]
	v_mfma_f32_16x16x32_bf16 v[64:67], v[156:159], v[206:209], v[64:67]
	v_mfma_f32_16x16x32_bf16 v[76:79], v[156:159], v[198:201], v[76:79]
	v_mfma_f32_16x16x32_bf16 v[76:79], v[152:155], v[194:197], v[76:79]
	v_mfma_f32_16x16x32_bf16 v[92:95], v[152:155], v[186:189], v[92:95]
	v_mfma_f32_16x16x32_bf16 v[92:95], v[156:159], v[190:193], v[92:95]
	v_mfma_f32_16x16x32_bf16 v[108:111], v[156:159], v[164:167], v[108:111]
	v_mfma_f32_16x16x32_bf16 v[108:111], v[152:155], v[160:163], v[108:111]
	s_barrier
	s_add_i32 s72, s83, s74
	v_lshl_add_u64 v[222:223], s[80:81], 0, v[184:185]
	s_mov_b32 m0, s72
	s_nop 0
	global_load_lds_dwordx4 v[222:223], off
	v_lshl_add_u64 v[224:225], v[222:223], 0, s[40:41]
	s_add_i32 m0, s72, 0x2000
	s_add_i32 s71, s71, s74
	global_load_lds_dwordx4 v[224:225], off
	v_lshl_add_u64 v[224:225], v[222:223], 0, s[4:5]
	s_mov_b32 m0, s71
	s_nop 0
	global_load_lds_dwordx4 v[224:225], off
	v_lshl_add_u64 v[224:225], v[222:223], 0, s[6:7]
	s_add_i32 m0, s71, 0x2000
	s_nop 0
	global_load_lds_dwordx4 v[224:225], off
	v_lshl_add_u64 v[224:225], s[42:43], 0, v[182:183]
	s_mov_b32 m0, s39
	v_lshl_add_u64 v[226:227], v[224:225], 0, s[40:41]
	global_load_lds_dwordx4 v[224:225], off
	s_mov_b32 m0, s75
	s_nop 0
	global_load_lds_dwordx4 v[226:227], off
	ds_read_b128 v[160:163], v221 offset:16384
	ds_read_b128 v[164:167], v221 offset:17408
	ds_read_b128 v[186:189], v221 offset:18432
	ds_read_b128 v[190:193], v221 offset:19456
	ds_read_b128 v[194:197], v221 offset:20480
	ds_read_b128 v[198:201], v221 offset:21504
	ds_read_b128 v[202:205], v221 offset:22528
	ds_read_b128 v[206:209], v221 offset:23552
	s_waitcnt vmcnt(8)
	s_waitcnt lgkmcnt(0)
	s_barrier
	s_waitcnt lgkmcnt(0)
	v_mfma_f32_16x16x32_bf16 v[60:63], v[128:131], v[160:163], v[60:63]
	v_mfma_f32_16x16x32_bf16 v[60:63], v[132:135], v[164:167], v[60:63]
	v_mfma_f32_16x16x32_bf16 v[48:51], v[132:135], v[190:193], v[48:51]
	v_mfma_f32_16x16x32_bf16 v[48:51], v[128:131], v[186:189], v[48:51]
	v_mfma_f32_16x16x32_bf16 v[32:35], v[128:131], v[194:197], v[32:35]
	v_mfma_f32_16x16x32_bf16 v[32:35], v[132:135], v[198:201], v[32:35]
	v_mfma_f32_16x16x32_bf16 v[16:19], v[132:135], v[206:209], v[16:19]
	v_mfma_f32_16x16x32_bf16 v[16:19], v[128:131], v[202:205], v[16:19]
	v_mfma_f32_16x16x32_bf16 v[8:11], v[136:139], v[202:205], v[8:11]
	v_mfma_f32_16x16x32_bf16 v[8:11], v[140:143], v[206:209], v[8:11]
	v_mfma_f32_16x16x32_bf16 v[24:27], v[140:143], v[198:201], v[24:27]
	v_mfma_f32_16x16x32_bf16 v[24:27], v[136:139], v[194:197], v[24:27]
	v_mfma_f32_16x16x32_bf16 v[40:43], v[136:139], v[186:189], v[40:43]
	v_mfma_f32_16x16x32_bf16 v[40:43], v[140:143], v[190:193], v[40:43]
	v_mfma_f32_16x16x32_bf16 v[56:59], v[140:143], v[164:167], v[56:59]
	v_mfma_f32_16x16x32_bf16 v[56:59], v[136:139], v[160:163], v[56:59]
	v_mfma_f32_16x16x32_bf16 v[52:55], v[144:147], v[160:163], v[52:55]
	v_mfma_f32_16x16x32_bf16 v[52:55], v[148:151], v[164:167], v[52:55]
	v_mfma_f32_16x16x32_bf16 v[36:39], v[148:151], v[190:193], v[36:39]
	v_mfma_f32_16x16x32_bf16 v[36:39], v[144:147], v[186:189], v[36:39]
	v_mfma_f32_16x16x32_bf16 v[20:23], v[144:147], v[194:197], v[20:23]
	v_mfma_f32_16x16x32_bf16 v[20:23], v[148:151], v[198:201], v[20:23]
	v_mfma_f32_16x16x32_bf16 v[4:7], v[148:151], v[206:209], v[4:7]
	v_mfma_f32_16x16x32_bf16 v[4:7], v[144:147], v[202:205], v[4:7]
	v_mfma_f32_16x16x32_bf16 v[0:3], v[152:155], v[202:205], v[0:3]
	v_mfma_f32_16x16x32_bf16 v[0:3], v[156:159], v[206:209], v[0:3]
	v_mfma_f32_16x16x32_bf16 v[12:15], v[156:159], v[198:201], v[12:15]
	v_mfma_f32_16x16x32_bf16 v[12:15], v[152:155], v[194:197], v[12:15]
	v_mfma_f32_16x16x32_bf16 v[28:31], v[152:155], v[186:189], v[28:31]
	v_mfma_f32_16x16x32_bf16 v[28:31], v[156:159], v[190:193], v[28:31]
	v_mfma_f32_16x16x32_bf16 v[44:47], v[156:159], v[164:167], v[44:47]
	v_mfma_f32_16x16x32_bf16 v[44:47], v[152:155], v[160:163], v[44:47]
	s_barrier
	s_add_i32 s42, 0, 0x18000
	s_add_i32 s43, 0, 0x1c000
	v_add_u32_e32 v140, s42, v220
	v_add_u32_e32 v156, s43, v220
	s_mov_b32 m0, s30
	v_lshl_add_u64 v[226:227], v[224:225], 0, s[4:5]
	global_load_lds_dwordx4 v[226:227], off
	v_lshl_add_u64 v[226:227], v[224:225], 0, s[6:7]
	s_mov_b32 m0, s31
	s_nop 0
	global_load_lds_dwordx4 v[226:227], off
	ds_read_b128 v[128:131], v140
	ds_read_b128 v[132:135], v140 offset:1024
	ds_read_b128 v[136:139], v140 offset:2048
	ds_read_b128 v[140:143], v140 offset:3072
	ds_read_b128 v[144:147], v156
	ds_read_b128 v[148:151], v156 offset:1024
	ds_read_b128 v[152:155], v156 offset:2048
	ds_read_b128 v[156:159], v156 offset:3072
	ds_read_b128 v[160:163], v221 offset:32768
	ds_read_b128 v[164:167], v221 offset:33792
	ds_read_b128 v[186:189], v221 offset:34816
	ds_read_b128 v[190:193], v221 offset:35840
	ds_read_b128 v[194:197], v221 offset:36864
	ds_read_b128 v[198:201], v221 offset:37888
	ds_read_b128 v[202:205], v221 offset:38912
	ds_read_b128 v[206:209], v221 offset:39936
	s_waitcnt vmcnt(8)
	s_waitcnt lgkmcnt(0)
	s_barrier
	s_waitcnt lgkmcnt(0)
	v_mfma_f32_16x16x32_bf16 v[124:127], v[128:131], v[160:163], v[124:127]
	v_mfma_f32_16x16x32_bf16 v[124:127], v[132:135], v[164:167], v[124:127]
	v_mfma_f32_16x16x32_bf16 v[112:115], v[132:135], v[190:193], v[112:115]
	v_mfma_f32_16x16x32_bf16 v[112:115], v[128:131], v[186:189], v[112:115]
	v_mfma_f32_16x16x32_bf16 v[96:99], v[128:131], v[194:197], v[96:99]
	v_mfma_f32_16x16x32_bf16 v[96:99], v[132:135], v[198:201], v[96:99]
	v_mfma_f32_16x16x32_bf16 v[80:83], v[132:135], v[206:209], v[80:83]
	v_mfma_f32_16x16x32_bf16 v[80:83], v[128:131], v[202:205], v[80:83]
	v_mfma_f32_16x16x32_bf16 v[72:75], v[136:139], v[202:205], v[72:75]
	v_mfma_f32_16x16x32_bf16 v[72:75], v[140:143], v[206:209], v[72:75]
	v_mfma_f32_16x16x32_bf16 v[88:91], v[140:143], v[198:201], v[88:91]
	v_mfma_f32_16x16x32_bf16 v[88:91], v[136:139], v[194:197], v[88:91]
	v_mfma_f32_16x16x32_bf16 v[104:107], v[136:139], v[186:189], v[104:107]
	v_mfma_f32_16x16x32_bf16 v[104:107], v[140:143], v[190:193], v[104:107]
	v_mfma_f32_16x16x32_bf16 v[120:123], v[140:143], v[164:167], v[120:123]
	v_mfma_f32_16x16x32_bf16 v[120:123], v[136:139], v[160:163], v[120:123]
	v_mfma_f32_16x16x32_bf16 v[116:119], v[144:147], v[160:163], v[116:119]
	v_mfma_f32_16x16x32_bf16 v[116:119], v[148:151], v[164:167], v[116:119]
	v_mfma_f32_16x16x32_bf16 v[100:103], v[148:151], v[190:193], v[100:103]
	v_mfma_f32_16x16x32_bf16 v[100:103], v[144:147], v[186:189], v[100:103]
	v_mfma_f32_16x16x32_bf16 v[84:87], v[144:147], v[194:197], v[84:87]
	v_mfma_f32_16x16x32_bf16 v[84:87], v[148:151], v[198:201], v[84:87]
	v_mfma_f32_16x16x32_bf16 v[68:71], v[148:151], v[206:209], v[68:71]
	v_mfma_f32_16x16x32_bf16 v[68:71], v[144:147], v[202:205], v[68:71]
	v_mfma_f32_16x16x32_bf16 v[64:67], v[152:155], v[202:205], v[64:67]
	v_mfma_f32_16x16x32_bf16 v[64:67], v[156:159], v[206:209], v[64:67]
	v_mfma_f32_16x16x32_bf16 v[76:79], v[156:159], v[198:201], v[76:79]
	v_mfma_f32_16x16x32_bf16 v[76:79], v[152:155], v[194:197], v[76:79]
	v_mfma_f32_16x16x32_bf16 v[92:95], v[152:155], v[186:189], v[92:95]
	v_mfma_f32_16x16x32_bf16 v[92:95], v[156:159], v[190:193], v[92:95]
	v_mfma_f32_16x16x32_bf16 v[108:111], v[156:159], v[164:167], v[108:111]
	v_mfma_f32_16x16x32_bf16 v[108:111], v[152:155], v[160:163], v[108:111]
	s_barrier
	s_add_i32 s42, s42, s74
	v_lshl_add_u64 v[226:227], v[222:223], 0, s[10:11]
	s_mov_b32 m0, s42
	s_nop 0
	global_load_lds_dwordx4 v[226:227], off
	v_lshl_add_u64 v[226:227], v[222:223], 0, s[12:13]
	s_add_i32 m0, s42, 0x2000
	s_add_i32 s42, s43, s74
	global_load_lds_dwordx4 v[226:227], off
	v_lshl_add_u64 v[226:227], v[222:223], 0, s[14:15]
	s_mov_b32 m0, s42
	v_lshl_add_u64 v[222:223], v[222:223], 0, s[16:17]
	global_load_lds_dwordx4 v[226:227], off
	s_add_i32 m0, s42, 0x2000
	s_nop 0
	global_load_lds_dwordx4 v[222:223], off
	v_lshl_add_u64 v[222:223], v[224:225], 0, s[10:11]
	s_mov_b32 m0, s26
	s_nop 0
	global_load_lds_dwordx4 v[222:223], off
	v_lshl_add_u64 v[222:223], v[224:225], 0, s[12:13]
	s_mov_b32 m0, s27
	s_nop 0
	global_load_lds_dwordx4 v[222:223], off
	ds_read_b128 v[160:163], v221 offset:49152
	ds_read_b128 v[164:167], v221 offset:50176
	ds_read_b128 v[186:189], v221 offset:51200
	ds_read_b128 v[190:193], v221 offset:52224
	ds_read_b128 v[194:197], v221 offset:53248
	ds_read_b128 v[198:201], v221 offset:54272
	ds_read_b128 v[202:205], v221 offset:55296
	ds_read_b128 v[206:209], v221 offset:56320
	s_waitcnt vmcnt(8)
	s_waitcnt lgkmcnt(0)
	s_barrier
	s_waitcnt lgkmcnt(0)
	v_mfma_f32_16x16x32_bf16 v[60:63], v[128:131], v[160:163], v[60:63]
	v_mfma_f32_16x16x32_bf16 v[60:63], v[132:135], v[164:167], v[60:63]
	v_mfma_f32_16x16x32_bf16 v[48:51], v[132:135], v[190:193], v[48:51]
	v_mfma_f32_16x16x32_bf16 v[48:51], v[128:131], v[186:189], v[48:51]
	v_mfma_f32_16x16x32_bf16 v[32:35], v[128:131], v[194:197], v[32:35]
	v_mfma_f32_16x16x32_bf16 v[32:35], v[132:135], v[198:201], v[32:35]
	v_mfma_f32_16x16x32_bf16 v[16:19], v[132:135], v[206:209], v[16:19]
	v_mfma_f32_16x16x32_bf16 v[16:19], v[128:131], v[202:205], v[16:19]
	v_mfma_f32_16x16x32_bf16 v[8:11], v[136:139], v[202:205], v[8:11]
	v_mfma_f32_16x16x32_bf16 v[8:11], v[140:143], v[206:209], v[8:11]
	v_mfma_f32_16x16x32_bf16 v[24:27], v[140:143], v[198:201], v[24:27]
	v_mfma_f32_16x16x32_bf16 v[24:27], v[136:139], v[194:197], v[24:27]
	v_mfma_f32_16x16x32_bf16 v[40:43], v[136:139], v[186:189], v[40:43]
	v_mfma_f32_16x16x32_bf16 v[40:43], v[140:143], v[190:193], v[40:43]
	v_mfma_f32_16x16x32_bf16 v[56:59], v[140:143], v[164:167], v[56:59]
	v_mfma_f32_16x16x32_bf16 v[56:59], v[136:139], v[160:163], v[56:59]
	v_mfma_f32_16x16x32_bf16 v[52:55], v[144:147], v[160:163], v[52:55]
	v_mfma_f32_16x16x32_bf16 v[52:55], v[148:151], v[164:167], v[52:55]
	v_mfma_f32_16x16x32_bf16 v[36:39], v[148:151], v[190:193], v[36:39]
	v_mfma_f32_16x16x32_bf16 v[36:39], v[144:147], v[186:189], v[36:39]
	v_mfma_f32_16x16x32_bf16 v[20:23], v[144:147], v[194:197], v[20:23]
	v_mfma_f32_16x16x32_bf16 v[20:23], v[148:151], v[198:201], v[20:23]
	v_mfma_f32_16x16x32_bf16 v[4:7], v[148:151], v[206:209], v[4:7]
	v_mfma_f32_16x16x32_bf16 v[4:7], v[144:147], v[202:205], v[4:7]
	v_mfma_f32_16x16x32_bf16 v[0:3], v[152:155], v[202:205], v[0:3]
	v_mfma_f32_16x16x32_bf16 v[0:3], v[156:159], v[206:209], v[0:3]
	v_mfma_f32_16x16x32_bf16 v[12:15], v[156:159], v[198:201], v[12:15]
	v_mfma_f32_16x16x32_bf16 v[12:15], v[152:155], v[194:197], v[12:15]
	v_mfma_f32_16x16x32_bf16 v[28:31], v[152:155], v[186:189], v[28:31]
	v_mfma_f32_16x16x32_bf16 v[28:31], v[156:159], v[190:193], v[28:31]
	v_mfma_f32_16x16x32_bf16 v[44:47], v[156:159], v[164:167], v[44:47]
	v_mfma_f32_16x16x32_bf16 v[44:47], v[152:155], v[160:163], v[44:47]
	s_barrier
	s_cmp_gt_u32 s70, 13
	s_cbranch_scc0 .LBB0_386
	s_and_b64 vcc, exec, s[58:59]
	s_cbranch_vccz .LBB0_389
	s_barrier

.LBB0_760:
	s_add_i32 s78, s78, 2
	s_mov_b32 s50, s78
	s_ashr_i32 s51, s50, 31
	s_lshl_b64 s[80:81], s[50:51], 7
	s_add_u32 s51, s80, 0x100
	s_addc_u32 s79, s81, 0
	s_add_u32 s82, s48, s51
	s_addc_u32 s83, s49, s79
	s_add_u32 s84, s8, s51
	s_addc_u32 s79, s9, s79
	s_add_i32 s85, 0, 0x10000
	s_cmp_eq_u32 s50, 14
	s_cselect_b32 s51, s35, s83
	s_cselect_b32 s50, s76, s82
	s_cselect_b32 s83, s31, s79
	s_cselect_b32 s82, s77, s84
	s_add_i32 s79, 0, 0x14000
	s_add_u32 s80, s48, s80
	s_addc_u32 s81, s49, s81
	v_lshl_add_u64 v[134:135], s[80:81], 0, v[128:129]
	v_lshl_add_u64 v[224:225], v[134:135], 0, s[14:15]
	s_add_i32 m0, s62, 0xc000
	s_nop 0
	global_load_lds_dwordx4 v[224:225], off
	v_lshl_add_u64 v[134:135], v[134:135], 0, s[16:17]
	s_add_i32 m0, s62, 0xe000
	s_nop 0
	global_load_lds_dwordx4 v[134:135], off
	v_add_u32_e32 v134, s85, v137
	ds_read_b128 v[130:133], v134
	ds_read_b128 v[140:143], v134 offset:1024
	ds_read_b128 v[144:147], v134 offset:2048
	ds_read_b128 v[148:151], v134 offset:3072
	v_add_u32_e32 v134, s79, v137
	ds_read_b128 v[152:155], v134
	ds_read_b128 v[156:159], v134 offset:1024
	ds_read_b128 v[160:163], v134 offset:2048
	ds_read_b128 v[164:167], v134 offset:3072
	ds_read_b128 v[182:185], v138
	ds_read_b128 v[186:189], v138 offset:1024
	ds_read_b128 v[190:193], v138 offset:2048
	ds_read_b128 v[194:197], v138 offset:3072
	ds_read_b128 v[198:201], v138 offset:4096
	ds_read_b128 v[202:205], v138 offset:5120
	ds_read_b128 v[206:209], v138 offset:6144
	ds_read_b128 v[220:223], v138 offset:7168
	s_nop 0
	s_waitcnt vmcnt(8)
	s_waitcnt lgkmcnt(0)
	s_barrier
	s_waitcnt lgkmcnt(0)
	v_mfma_f32_16x16x32_bf16 v[124:127], v[130:133], v[182:185], v[124:127]
	v_mfma_f32_16x16x32_bf16 v[124:127], v[140:143], v[186:189], v[124:127]
	v_mfma_f32_16x16x32_bf16 v[108:111], v[140:143], v[194:197], v[108:111]
	v_mfma_f32_16x16x32_bf16 v[108:111], v[130:133], v[190:193], v[108:111]
	v_mfma_f32_16x16x32_bf16 v[92:95], v[130:133], v[198:201], v[92:95]
	v_mfma_f32_16x16x32_bf16 v[92:95], v[140:143], v[202:205], v[92:95]
	v_mfma_f32_16x16x32_bf16 v[76:79], v[140:143], v[220:223], v[76:79]
	v_mfma_f32_16x16x32_bf16 v[76:79], v[130:133], v[206:209], v[76:79]
	v_mfma_f32_16x16x32_bf16 v[72:75], v[144:147], v[206:209], v[72:75]
	v_mfma_f32_16x16x32_bf16 v[72:75], v[148:151], v[220:223], v[72:75]
	v_mfma_f32_16x16x32_bf16 v[88:91], v[148:151], v[202:205], v[88:91]
	v_mfma_f32_16x16x32_bf16 v[88:91], v[144:147], v[198:201], v[88:91]
	v_mfma_f32_16x16x32_bf16 v[104:107], v[144:147], v[190:193], v[104:107]
	v_mfma_f32_16x16x32_bf16 v[104:107], v[148:151], v[194:197], v[104:107]
	v_mfma_f32_16x16x32_bf16 v[120:123], v[148:151], v[186:189], v[120:123]
	v_mfma_f32_16x16x32_bf16 v[120:123], v[144:147], v[182:185], v[120:123]
	v_mfma_f32_16x16x32_bf16 v[116:119], v[152:155], v[182:185], v[116:119]
	v_mfma_f32_16x16x32_bf16 v[116:119], v[156:159], v[186:189], v[116:119]
	v_mfma_f32_16x16x32_bf16 v[100:103], v[156:159], v[194:197], v[100:103]
	v_mfma_f32_16x16x32_bf16 v[100:103], v[152:155], v[190:193], v[100:103]
	v_mfma_f32_16x16x32_bf16 v[84:87], v[152:155], v[198:201], v[84:87]
	v_mfma_f32_16x16x32_bf16 v[84:87], v[156:159], v[202:205], v[84:87]
	v_mfma_f32_16x16x32_bf16 v[68:71], v[156:159], v[220:223], v[68:71]
	v_mfma_f32_16x16x32_bf16 v[68:71], v[152:155], v[206:209], v[68:71]
	v_mfma_f32_16x16x32_bf16 v[64:67], v[160:163], v[206:209], v[64:67]
	v_mfma_f32_16x16x32_bf16 v[64:67], v[164:167], v[220:223], v[64:67]
	v_mfma_f32_16x16x32_bf16 v[80:83], v[164:167], v[202:205], v[80:83]
	v_mfma_f32_16x16x32_bf16 v[80:83], v[160:163], v[198:201], v[80:83]
	v_mfma_f32_16x16x32_bf16 v[96:99], v[160:163], v[190:193], v[96:99]
	v_mfma_f32_16x16x32_bf16 v[96:99], v[164:167], v[194:197], v[96:99]
	v_mfma_f32_16x16x32_bf16 v[112:115], v[164:167], v[186:189], v[112:115]
	v_mfma_f32_16x16x32_bf16 v[112:115], v[160:163], v[182:185], v[112:115]
	s_barrier
	s_add_i32 s80, s85, s59
	v_lshl_add_u64 v[134:135], s[82:83], 0, v[172:173]
	s_mov_b32 m0, s80
	s_nop 0
	global_load_lds_dwordx4 v[134:135], off
	v_lshl_add_u64 v[224:225], v[134:135], 0, s[40:41]
	s_add_i32 m0, s80, 0x2000
	s_add_i32 s79, s79, s59
	global_load_lds_dwordx4 v[224:225], off
	v_lshl_add_u64 v[224:225], v[134:135], 0, s[4:5]
	s_mov_b32 m0, s79
	s_nop 0
	global_load_lds_dwordx4 v[224:225], off
	v_lshl_add_u64 v[224:225], v[134:135], 0, s[6:7]
	s_add_i32 m0, s79, 0x2000
	s_nop 0
	global_load_lds_dwordx4 v[224:225], off
	v_lshl_add_u64 v[224:225], s[50:51], 0, v[128:129]
	s_mov_b32 m0, s62
	v_lshl_add_u64 v[226:227], v[224:225], 0, s[40:41]
	global_load_lds_dwordx4 v[224:225], off
	s_mov_b32 m0, s63
	s_nop 0
	global_load_lds_dwordx4 v[226:227], off
	ds_read_b128 v[182:185], v138 offset:16384
	ds_read_b128 v[186:189], v138 offset:17408
	ds_read_b128 v[190:193], v138 offset:18432
	ds_read_b128 v[194:197], v138 offset:19456
	ds_read_b128 v[198:201], v138 offset:20480
	ds_read_b128 v[202:205], v138 offset:21504
	ds_read_b128 v[206:209], v138 offset:22528
	ds_read_b128 v[220:223], v138 offset:23552
	s_waitcnt vmcnt(8)
	s_waitcnt lgkmcnt(0)
	s_barrier
	s_waitcnt lgkmcnt(0)
	v_mfma_f32_16x16x32_bf16 v[60:63], v[130:133], v[182:185], v[60:63]
	v_mfma_f32_16x16x32_bf16 v[60:63], v[140:143], v[186:189], v[60:63]
	v_mfma_f32_16x16x32_bf16 v[44:47], v[140:143], v[194:197], v[44:47]
	v_mfma_f32_16x16x32_bf16 v[44:47], v[130:133], v[190:193], v[44:47]
	v_mfma_f32_16x16x32_bf16 v[28:31], v[130:133], v[198:201], v[28:31]
	v_mfma_f32_16x16x32_bf16 v[28:31], v[140:143], v[202:205], v[28:31]
	v_mfma_f32_16x16x32_bf16 v[12:15], v[140:143], v[220:223], v[12:15]
	v_mfma_f32_16x16x32_bf16 v[12:15], v[130:133], v[206:209], v[12:15]
	v_mfma_f32_16x16x32_bf16 v[8:11], v[144:147], v[206:209], v[8:11]
	v_mfma_f32_16x16x32_bf16 v[8:11], v[148:151], v[220:223], v[8:11]
	v_mfma_f32_16x16x32_bf16 v[24:27], v[148:151], v[202:205], v[24:27]
	v_mfma_f32_16x16x32_bf16 v[24:27], v[144:147], v[198:201], v[24:27]
	v_mfma_f32_16x16x32_bf16 v[40:43], v[144:147], v[190:193], v[40:43]
	v_mfma_f32_16x16x32_bf16 v[40:43], v[148:151], v[194:197], v[40:43]
	v_mfma_f32_16x16x32_bf16 v[56:59], v[148:151], v[186:189], v[56:59]
	v_mfma_f32_16x16x32_bf16 v[56:59], v[144:147], v[182:185], v[56:59]
	v_mfma_f32_16x16x32_bf16 v[52:55], v[152:155], v[182:185], v[52:55]
	v_mfma_f32_16x16x32_bf16 v[52:55], v[156:159], v[186:189], v[52:55]
	v_mfma_f32_16x16x32_bf16 v[36:39], v[156:159], v[194:197], v[36:39]
	v_mfma_f32_16x16x32_bf16 v[36:39], v[152:155], v[190:193], v[36:39]
	v_mfma_f32_16x16x32_bf16 v[20:23], v[152:155], v[198:201], v[20:23]
	v_mfma_f32_16x16x32_bf16 v[20:23], v[156:159], v[202:205], v[20:23]
	v_mfma_f32_16x16x32_bf16 v[4:7], v[156:159], v[220:223], v[4:7]
	v_mfma_f32_16x16x32_bf16 v[4:7], v[152:155], v[206:209], v[4:7]
	v_mfma_f32_16x16x32_bf16 v[0:3], v[160:163], v[206:209], v[0:3]
	v_mfma_f32_16x16x32_bf16 v[0:3], v[164:167], v[220:223], v[0:3]
	v_mfma_f32_16x16x32_bf16 v[16:19], v[164:167], v[202:205], v[16:19]
	v_mfma_f32_16x16x32_bf16 v[16:19], v[160:163], v[198:201], v[16:19]
	v_mfma_f32_16x16x32_bf16 v[32:35], v[160:163], v[190:193], v[32:35]
	v_mfma_f32_16x16x32_bf16 v[32:35], v[164:167], v[194:197], v[32:35]
	v_mfma_f32_16x16x32_bf16 v[48:51], v[164:167], v[186:189], v[48:51]
	v_mfma_f32_16x16x32_bf16 v[48:51], v[160:163], v[182:185], v[48:51]
	s_barrier
	s_mov_b32 m0, s68
	v_lshl_add_u64 v[226:227], v[224:225], 0, s[4:5]
	global_load_lds_dwordx4 v[226:227], off
	v_lshl_add_u64 v[226:227], v[224:225], 0, s[6:7]
	s_mov_b32 m0, s69
	s_nop 0
	global_load_lds_dwordx4 v[226:227], off
	s_add_i32 s50, 0, 0x18000
	v_add_u32_e32 v139, s50, v137
	s_add_i32 s51, 0, 0x1c000
	ds_read_b128 v[130:133], v139
	ds_read_b128 v[140:143], v139 offset:1024
	ds_read_b128 v[144:147], v139 offset:2048
	ds_read_b128 v[148:151], v139 offset:3072
	v_add_u32_e32 v139, s51, v137
	ds_read_b128 v[152:155], v139
	ds_read_b128 v[156:159], v139 offset:1024
	ds_read_b128 v[160:163], v139 offset:2048
	ds_read_b128 v[164:167], v139 offset:3072
	ds_read_b128 v[182:185], v138 offset:32768
	ds_read_b128 v[186:189], v138 offset:33792
	ds_read_b128 v[190:193], v138 offset:34816
	ds_read_b128 v[194:197], v138 offset:35840
	ds_read_b128 v[198:201], v138 offset:36864
	ds_read_b128 v[202:205], v138 offset:37888
	ds_read_b128 v[206:209], v138 offset:38912
	ds_read_b128 v[220:223], v138 offset:39936
	s_nop 0
	s_waitcnt vmcnt(8)
	s_waitcnt lgkmcnt(0)
	s_barrier
	s_waitcnt lgkmcnt(0)
	v_mfma_f32_16x16x32_bf16 v[124:127], v[130:133], v[182:185], v[124:127]
	v_mfma_f32_16x16x32_bf16 v[124:127], v[140:143], v[186:189], v[124:127]
	v_mfma_f32_16x16x32_bf16 v[108:111], v[140:143], v[194:197], v[108:111]
	v_mfma_f32_16x16x32_bf16 v[108:111], v[130:133], v[190:193], v[108:111]
	v_mfma_f32_16x16x32_bf16 v[92:95], v[130:133], v[198:201], v[92:95]
	v_mfma_f32_16x16x32_bf16 v[92:95], v[140:143], v[202:205], v[92:95]
	v_mfma_f32_16x16x32_bf16 v[76:79], v[140:143], v[220:223], v[76:79]
	v_mfma_f32_16x16x32_bf16 v[76:79], v[130:133], v[206:209], v[76:79]
	v_mfma_f32_16x16x32_bf16 v[72:75], v[144:147], v[206:209], v[72:75]
	v_mfma_f32_16x16x32_bf16 v[72:75], v[148:151], v[220:223], v[72:75]
	v_mfma_f32_16x16x32_bf16 v[88:91], v[148:151], v[202:205], v[88:91]
	v_mfma_f32_16x16x32_bf16 v[88:91], v[144:147], v[198:201], v[88:91]
	v_mfma_f32_16x16x32_bf16 v[104:107], v[144:147], v[190:193], v[104:107]
	v_mfma_f32_16x16x32_bf16 v[104:107], v[148:151], v[194:197], v[104:107]
	v_mfma_f32_16x16x32_bf16 v[120:123], v[148:151], v[186:189], v[120:123]
	v_mfma_f32_16x16x32_bf16 v[120:123], v[144:147], v[182:185], v[120:123]
	v_mfma_f32_16x16x32_bf16 v[116:119], v[152:155], v[182:185], v[116:119]
	v_mfma_f32_16x16x32_bf16 v[116:119], v[156:159], v[186:189], v[116:119]
	v_mfma_f32_16x16x32_bf16 v[100:103], v[156:159], v[194:197], v[100:103]
	v_mfma_f32_16x16x32_bf16 v[100:103], v[152:155], v[190:193], v[100:103]
	v_mfma_f32_16x16x32_bf16 v[84:87], v[152:155], v[198:201], v[84:87]
	v_mfma_f32_16x16x32_bf16 v[84:87], v[156:159], v[202:205], v[84:87]
	v_mfma_f32_16x16x32_bf16 v[68:71], v[156:159], v[220:223], v[68:71]
	v_mfma_f32_16x16x32_bf16 v[68:71], v[152:155], v[206:209], v[68:71]
	v_mfma_f32_16x16x32_bf16 v[64:67], v[160:163], v[206:209], v[64:67]
	v_mfma_f32_16x16x32_bf16 v[64:67], v[164:167], v[220:223], v[64:67]
	v_mfma_f32_16x16x32_bf16 v[80:83], v[164:167], v[202:205], v[80:83]
	v_mfma_f32_16x16x32_bf16 v[80:83], v[160:163], v[198:201], v[80:83]
	v_mfma_f32_16x16x32_bf16 v[96:99], v[160:163], v[190:193], v[96:99]
	v_mfma_f32_16x16x32_bf16 v[96:99], v[164:167], v[194:197], v[96:99]
	v_mfma_f32_16x16x32_bf16 v[112:115], v[164:167], v[186:189], v[112:115]
	v_mfma_f32_16x16x32_bf16 v[112:115], v[160:163], v[182:185], v[112:115]
	s_barrier
	s_add_i32 s50, s50, s59
	v_lshl_add_u64 v[226:227], v[134:135], 0, s[10:11]
	s_mov_b32 m0, s50
	s_nop 0
	global_load_lds_dwordx4 v[226:227], off
	v_lshl_add_u64 v[226:227], v[134:135], 0, s[12:13]
	s_add_i32 m0, s50, 0x2000
	s_add_i32 s50, s51, s59
	global_load_lds_dwordx4 v[226:227], off
	v_lshl_add_u64 v[226:227], v[134:135], 0, s[14:15]
	s_mov_b32 m0, s50
	v_lshl_add_u64 v[134:135], v[134:135], 0, s[16:17]
	global_load_lds_dwordx4 v[226:227], off
	s_add_i32 m0, s50, 0x2000
	s_nop 0
	global_load_lds_dwordx4 v[134:135], off
	v_lshl_add_u64 v[134:135], v[224:225], 0, s[10:11]
	s_mov_b32 m0, s72
	s_nop 0
	global_load_lds_dwordx4 v[134:135], off
	v_lshl_add_u64 v[134:135], v[224:225], 0, s[12:13]
	s_mov_b32 m0, s73
	s_nop 0
	global_load_lds_dwordx4 v[134:135], off
	ds_read_b128 v[182:185], v138 offset:49152
	ds_read_b128 v[186:189], v138 offset:50176
	ds_read_b128 v[190:193], v138 offset:51200
	ds_read_b128 v[194:197], v138 offset:52224
	ds_read_b128 v[198:201], v138 offset:53248
	ds_read_b128 v[202:205], v138 offset:54272
	ds_read_b128 v[206:209], v138 offset:55296
	ds_read_b128 v[220:223], v138 offset:56320
	s_waitcnt vmcnt(8)
	s_waitcnt lgkmcnt(0)
	s_barrier
	s_waitcnt lgkmcnt(0)
	v_mfma_f32_16x16x32_bf16 v[60:63], v[130:133], v[182:185], v[60:63]
	v_mfma_f32_16x16x32_bf16 v[60:63], v[140:143], v[186:189], v[60:63]
	v_mfma_f32_16x16x32_bf16 v[44:47], v[140:143], v[194:197], v[44:47]
	v_mfma_f32_16x16x32_bf16 v[44:47], v[130:133], v[190:193], v[44:47]
	v_mfma_f32_16x16x32_bf16 v[28:31], v[130:133], v[198:201], v[28:31]
	v_mfma_f32_16x16x32_bf16 v[28:31], v[140:143], v[202:205], v[28:31]
	v_mfma_f32_16x16x32_bf16 v[12:15], v[140:143], v[220:223], v[12:15]
	v_mfma_f32_16x16x32_bf16 v[12:15], v[130:133], v[206:209], v[12:15]
	v_mfma_f32_16x16x32_bf16 v[8:11], v[144:147], v[206:209], v[8:11]
	v_mfma_f32_16x16x32_bf16 v[8:11], v[148:151], v[220:223], v[8:11]
	v_mfma_f32_16x16x32_bf16 v[24:27], v[148:151], v[202:205], v[24:27]
	v_mfma_f32_16x16x32_bf16 v[24:27], v[144:147], v[198:201], v[24:27]
	v_mfma_f32_16x16x32_bf16 v[40:43], v[144:147], v[190:193], v[40:43]
	v_mfma_f32_16x16x32_bf16 v[40:43], v[148:151], v[194:197], v[40:43]
	v_mfma_f32_16x16x32_bf16 v[56:59], v[148:151], v[186:189], v[56:59]
	v_mfma_f32_16x16x32_bf16 v[56:59], v[144:147], v[182:185], v[56:59]
	v_mfma_f32_16x16x32_bf16 v[52:55], v[152:155], v[182:185], v[52:55]
	v_mfma_f32_16x16x32_bf16 v[52:55], v[156:159], v[186:189], v[52:55]
	v_mfma_f32_16x16x32_bf16 v[36:39], v[156:159], v[194:197], v[36:39]
	v_mfma_f32_16x16x32_bf16 v[36:39], v[152:155], v[190:193], v[36:39]
	v_mfma_f32_16x16x32_bf16 v[20:23], v[152:155], v[198:201], v[20:23]
	v_mfma_f32_16x16x32_bf16 v[20:23], v[156:159], v[202:205], v[20:23]
	v_mfma_f32_16x16x32_bf16 v[4:7], v[156:159], v[220:223], v[4:7]
	v_mfma_f32_16x16x32_bf16 v[4:7], v[152:155], v[206:209], v[4:7]
	v_mfma_f32_16x16x32_bf16 v[0:3], v[160:163], v[206:209], v[0:3]
	v_mfma_f32_16x16x32_bf16 v[0:3], v[164:167], v[220:223], v[0:3]
	v_mfma_f32_16x16x32_bf16 v[16:19], v[164:167], v[202:205], v[16:19]
	v_mfma_f32_16x16x32_bf16 v[16:19], v[160:163], v[198:201], v[16:19]
	v_mfma_f32_16x16x32_bf16 v[32:35], v[160:163], v[190:193], v[32:35]
	v_mfma_f32_16x16x32_bf16 v[32:35], v[164:167], v[194:197], v[32:35]
	v_mfma_f32_16x16x32_bf16 v[48:51], v[164:167], v[186:189], v[48:51]
	v_mfma_f32_16x16x32_bf16 v[48:51], v[160:163], v[182:185], v[48:51]
	s_barrier
	s_cmp_gt_u32 s78, 13
	s_cbranch_scc0 .LBB0_760
	s_and_b64 vcc, exec, s[28:29]
	s_cbranch_vccz .LBB0_763
	s_barrier

.LBB0_784:
	s_add_i32 s80, s80, 2
	s_mov_b32 s48, s80
	s_ashr_i32 s49, s48, 31
	s_lshl_b64 s[82:83], s[48:49], 7
	s_add_u32 s49, s82, 0x100
	s_addc_u32 s81, s83, 0
	s_add_u32 s84, s42, s49
	s_addc_u32 s85, s43, s81
	s_add_u32 s86, s8, s49
	s_addc_u32 s81, s9, s81
	s_add_i32 s87, 0, 0x10000
	s_cmp_eq_u32 s48, 14
	s_cselect_b32 s49, s39, s85
	s_cselect_b32 s48, s72, s84
	s_cselect_b32 s85, s35, s81
	s_cselect_b32 s84, s73, s86
	s_add_i32 s81, 0, 0x14000
	s_add_u32 s82, s42, s82
	s_addc_u32 s83, s43, s83
	v_lshl_add_u64 v[134:135], s[82:83], 0, v[128:129]
	v_lshl_add_u64 v[224:225], v[134:135], 0, s[14:15]
	s_add_i32 m0, s74, 0xc000
	s_nop 0
	global_load_lds_dwordx4 v[224:225], off
	v_lshl_add_u64 v[134:135], v[134:135], 0, s[16:17]
	s_add_i32 m0, s74, 0xe000
	s_nop 0
	global_load_lds_dwordx4 v[134:135], off
	v_add_u32_e32 v134, s87, v137
	ds_read_b128 v[130:133], v134
	ds_read_b128 v[140:143], v134 offset:1024
	ds_read_b128 v[144:147], v134 offset:2048
	ds_read_b128 v[148:151], v134 offset:3072
	v_add_u32_e32 v134, s81, v137
	ds_read_b128 v[152:155], v134
	ds_read_b128 v[156:159], v134 offset:1024
	ds_read_b128 v[160:163], v134 offset:2048
	ds_read_b128 v[164:167], v134 offset:3072
	ds_read_b128 v[182:185], v138
	ds_read_b128 v[186:189], v138 offset:1024
	ds_read_b128 v[190:193], v138 offset:2048
	ds_read_b128 v[194:197], v138 offset:3072
	ds_read_b128 v[198:201], v138 offset:4096
	ds_read_b128 v[202:205], v138 offset:5120
	ds_read_b128 v[206:209], v138 offset:6144
	ds_read_b128 v[220:223], v138 offset:7168
	s_nop 0
	s_waitcnt vmcnt(8)
	s_waitcnt lgkmcnt(0)
	s_barrier
	s_waitcnt lgkmcnt(0)
	v_mfma_f32_16x16x32_bf16 v[124:127], v[130:133], v[182:185], v[124:127]
	v_mfma_f32_16x16x32_bf16 v[124:127], v[140:143], v[186:189], v[124:127]
	v_mfma_f32_16x16x32_bf16 v[108:111], v[140:143], v[194:197], v[108:111]
	v_mfma_f32_16x16x32_bf16 v[108:111], v[130:133], v[190:193], v[108:111]
	v_mfma_f32_16x16x32_bf16 v[92:95], v[130:133], v[198:201], v[92:95]
	v_mfma_f32_16x16x32_bf16 v[92:95], v[140:143], v[202:205], v[92:95]
	v_mfma_f32_16x16x32_bf16 v[76:79], v[140:143], v[220:223], v[76:79]
	v_mfma_f32_16x16x32_bf16 v[76:79], v[130:133], v[206:209], v[76:79]
	v_mfma_f32_16x16x32_bf16 v[72:75], v[144:147], v[206:209], v[72:75]
	v_mfma_f32_16x16x32_bf16 v[72:75], v[148:151], v[220:223], v[72:75]
	v_mfma_f32_16x16x32_bf16 v[88:91], v[148:151], v[202:205], v[88:91]
	v_mfma_f32_16x16x32_bf16 v[88:91], v[144:147], v[198:201], v[88:91]
	v_mfma_f32_16x16x32_bf16 v[104:107], v[144:147], v[190:193], v[104:107]
	v_mfma_f32_16x16x32_bf16 v[104:107], v[148:151], v[194:197], v[104:107]
	v_mfma_f32_16x16x32_bf16 v[120:123], v[148:151], v[186:189], v[120:123]
	v_mfma_f32_16x16x32_bf16 v[120:123], v[144:147], v[182:185], v[120:123]
	v_mfma_f32_16x16x32_bf16 v[116:119], v[152:155], v[182:185], v[116:119]
	v_mfma_f32_16x16x32_bf16 v[116:119], v[156:159], v[186:189], v[116:119]
	v_mfma_f32_16x16x32_bf16 v[100:103], v[156:159], v[194:197], v[100:103]
	v_mfma_f32_16x16x32_bf16 v[100:103], v[152:155], v[190:193], v[100:103]
	v_mfma_f32_16x16x32_bf16 v[84:87], v[152:155], v[198:201], v[84:87]
	v_mfma_f32_16x16x32_bf16 v[84:87], v[156:159], v[202:205], v[84:87]
	v_mfma_f32_16x16x32_bf16 v[68:71], v[156:159], v[220:223], v[68:71]
	v_mfma_f32_16x16x32_bf16 v[68:71], v[152:155], v[206:209], v[68:71]
	v_mfma_f32_16x16x32_bf16 v[64:67], v[160:163], v[206:209], v[64:67]
	v_mfma_f32_16x16x32_bf16 v[64:67], v[164:167], v[220:223], v[64:67]
	v_mfma_f32_16x16x32_bf16 v[80:83], v[164:167], v[202:205], v[80:83]
	v_mfma_f32_16x16x32_bf16 v[80:83], v[160:163], v[198:201], v[80:83]
	v_mfma_f32_16x16x32_bf16 v[96:99], v[160:163], v[190:193], v[96:99]
	v_mfma_f32_16x16x32_bf16 v[96:99], v[164:167], v[194:197], v[96:99]
	v_mfma_f32_16x16x32_bf16 v[112:115], v[164:167], v[186:189], v[112:115]
	v_mfma_f32_16x16x32_bf16 v[112:115], v[160:163], v[182:185], v[112:115]
	s_barrier
	s_add_i32 s82, s87, s63
	v_lshl_add_u64 v[134:135], s[84:85], 0, v[172:173]
	s_mov_b32 m0, s82
	s_nop 0
	global_load_lds_dwordx4 v[134:135], off
	v_lshl_add_u64 v[224:225], v[134:135], 0, s[40:41]
	s_add_i32 m0, s82, 0x2000
	s_add_i32 s81, s81, s63
	global_load_lds_dwordx4 v[224:225], off
	v_lshl_add_u64 v[224:225], v[134:135], 0, s[4:5]
	s_mov_b32 m0, s81
	s_nop 0
	global_load_lds_dwordx4 v[224:225], off
	v_lshl_add_u64 v[224:225], v[134:135], 0, s[6:7]
	s_add_i32 m0, s81, 0x2000
	s_nop 0
	global_load_lds_dwordx4 v[224:225], off
	v_lshl_add_u64 v[224:225], s[48:49], 0, v[128:129]
	s_mov_b32 m0, s74
	v_lshl_add_u64 v[226:227], v[224:225], 0, s[40:41]
	global_load_lds_dwordx4 v[224:225], off
	s_mov_b32 m0, s75
	s_nop 0
	global_load_lds_dwordx4 v[226:227], off
	ds_read_b128 v[182:185], v138 offset:16384
	ds_read_b128 v[186:189], v138 offset:17408
	ds_read_b128 v[190:193], v138 offset:18432
	ds_read_b128 v[194:197], v138 offset:19456
	ds_read_b128 v[198:201], v138 offset:20480
	ds_read_b128 v[202:205], v138 offset:21504
	ds_read_b128 v[206:209], v138 offset:22528
	ds_read_b128 v[220:223], v138 offset:23552
	s_waitcnt vmcnt(8)
	s_waitcnt lgkmcnt(0)
	s_barrier
	s_waitcnt lgkmcnt(0)
	v_mfma_f32_16x16x32_bf16 v[60:63], v[130:133], v[182:185], v[60:63]
	v_mfma_f32_16x16x32_bf16 v[60:63], v[140:143], v[186:189], v[60:63]
	v_mfma_f32_16x16x32_bf16 v[44:47], v[140:143], v[194:197], v[44:47]
	v_mfma_f32_16x16x32_bf16 v[44:47], v[130:133], v[190:193], v[44:47]
	v_mfma_f32_16x16x32_bf16 v[28:31], v[130:133], v[198:201], v[28:31]
	v_mfma_f32_16x16x32_bf16 v[28:31], v[140:143], v[202:205], v[28:31]
	v_mfma_f32_16x16x32_bf16 v[12:15], v[140:143], v[220:223], v[12:15]
	v_mfma_f32_16x16x32_bf16 v[12:15], v[130:133], v[206:209], v[12:15]
	v_mfma_f32_16x16x32_bf16 v[8:11], v[144:147], v[206:209], v[8:11]
	v_mfma_f32_16x16x32_bf16 v[8:11], v[148:151], v[220:223], v[8:11]
	v_mfma_f32_16x16x32_bf16 v[24:27], v[148:151], v[202:205], v[24:27]
	v_mfma_f32_16x16x32_bf16 v[24:27], v[144:147], v[198:201], v[24:27]
	v_mfma_f32_16x16x32_bf16 v[40:43], v[144:147], v[190:193], v[40:43]
	v_mfma_f32_16x16x32_bf16 v[40:43], v[148:151], v[194:197], v[40:43]
	v_mfma_f32_16x16x32_bf16 v[56:59], v[148:151], v[186:189], v[56:59]
	v_mfma_f32_16x16x32_bf16 v[56:59], v[144:147], v[182:185], v[56:59]
	v_mfma_f32_16x16x32_bf16 v[52:55], v[152:155], v[182:185], v[52:55]
	v_mfma_f32_16x16x32_bf16 v[52:55], v[156:159], v[186:189], v[52:55]
	v_mfma_f32_16x16x32_bf16 v[36:39], v[156:159], v[194:197], v[36:39]
	v_mfma_f32_16x16x32_bf16 v[36:39], v[152:155], v[190:193], v[36:39]
	v_mfma_f32_16x16x32_bf16 v[20:23], v[152:155], v[198:201], v[20:23]
	v_mfma_f32_16x16x32_bf16 v[20:23], v[156:159], v[202:205], v[20:23]
	v_mfma_f32_16x16x32_bf16 v[4:7], v[156:159], v[220:223], v[4:7]
	v_mfma_f32_16x16x32_bf16 v[4:7], v[152:155], v[206:209], v[4:7]
	v_mfma_f32_16x16x32_bf16 v[0:3], v[160:163], v[206:209], v[0:3]
	v_mfma_f32_16x16x32_bf16 v[0:3], v[164:167], v[220:223], v[0:3]
	v_mfma_f32_16x16x32_bf16 v[16:19], v[164:167], v[202:205], v[16:19]
	v_mfma_f32_16x16x32_bf16 v[16:19], v[160:163], v[198:201], v[16:19]
	v_mfma_f32_16x16x32_bf16 v[32:35], v[160:163], v[190:193], v[32:35]
	v_mfma_f32_16x16x32_bf16 v[32:35], v[164:167], v[194:197], v[32:35]
	v_mfma_f32_16x16x32_bf16 v[48:51], v[164:167], v[186:189], v[48:51]
	v_mfma_f32_16x16x32_bf16 v[48:51], v[160:163], v[182:185], v[48:51]
	s_barrier
	s_mov_b32 m0, s76
	v_lshl_add_u64 v[226:227], v[224:225], 0, s[4:5]
	global_load_lds_dwordx4 v[226:227], off
	v_lshl_add_u64 v[226:227], v[224:225], 0, s[6:7]
	s_mov_b32 m0, s77
	s_nop 0
	global_load_lds_dwordx4 v[226:227], off
	s_add_i32 s48, 0, 0x18000
	v_add_u32_e32 v139, s48, v137
	s_add_i32 s49, 0, 0x1c000
	ds_read_b128 v[130:133], v139
	ds_read_b128 v[140:143], v139 offset:1024
	ds_read_b128 v[144:147], v139 offset:2048
	ds_read_b128 v[148:151], v139 offset:3072
	v_add_u32_e32 v139, s49, v137
	ds_read_b128 v[152:155], v139
	ds_read_b128 v[156:159], v139 offset:1024
	ds_read_b128 v[160:163], v139 offset:2048
	ds_read_b128 v[164:167], v139 offset:3072
	ds_read_b128 v[182:185], v138 offset:32768
	ds_read_b128 v[186:189], v138 offset:33792
	ds_read_b128 v[190:193], v138 offset:34816
	ds_read_b128 v[194:197], v138 offset:35840
	ds_read_b128 v[198:201], v138 offset:36864
	ds_read_b128 v[202:205], v138 offset:37888
	ds_read_b128 v[206:209], v138 offset:38912
	ds_read_b128 v[220:223], v138 offset:39936
	s_nop 0
	s_waitcnt vmcnt(8)
	s_waitcnt lgkmcnt(0)
	s_barrier
	s_waitcnt lgkmcnt(0)
	v_mfma_f32_16x16x32_bf16 v[124:127], v[130:133], v[182:185], v[124:127]
	v_mfma_f32_16x16x32_bf16 v[124:127], v[140:143], v[186:189], v[124:127]
	v_mfma_f32_16x16x32_bf16 v[108:111], v[140:143], v[194:197], v[108:111]
	v_mfma_f32_16x16x32_bf16 v[108:111], v[130:133], v[190:193], v[108:111]
	v_mfma_f32_16x16x32_bf16 v[92:95], v[130:133], v[198:201], v[92:95]
	v_mfma_f32_16x16x32_bf16 v[92:95], v[140:143], v[202:205], v[92:95]
	v_mfma_f32_16x16x32_bf16 v[76:79], v[140:143], v[220:223], v[76:79]
	v_mfma_f32_16x16x32_bf16 v[76:79], v[130:133], v[206:209], v[76:79]
	v_mfma_f32_16x16x32_bf16 v[72:75], v[144:147], v[206:209], v[72:75]
	v_mfma_f32_16x16x32_bf16 v[72:75], v[148:151], v[220:223], v[72:75]
	v_mfma_f32_16x16x32_bf16 v[88:91], v[148:151], v[202:205], v[88:91]
	v_mfma_f32_16x16x32_bf16 v[88:91], v[144:147], v[198:201], v[88:91]
	v_mfma_f32_16x16x32_bf16 v[104:107], v[144:147], v[190:193], v[104:107]
	v_mfma_f32_16x16x32_bf16 v[104:107], v[148:151], v[194:197], v[104:107]
	v_mfma_f32_16x16x32_bf16 v[120:123], v[148:151], v[186:189], v[120:123]
	v_mfma_f32_16x16x32_bf16 v[120:123], v[144:147], v[182:185], v[120:123]
	v_mfma_f32_16x16x32_bf16 v[116:119], v[152:155], v[182:185], v[116:119]
	v_mfma_f32_16x16x32_bf16 v[116:119], v[156:159], v[186:189], v[116:119]
	v_mfma_f32_16x16x32_bf16 v[100:103], v[156:159], v[194:197], v[100:103]
	v_mfma_f32_16x16x32_bf16 v[100:103], v[152:155], v[190:193], v[100:103]
	v_mfma_f32_16x16x32_bf16 v[84:87], v[152:155], v[198:201], v[84:87]
	v_mfma_f32_16x16x32_bf16 v[84:87], v[156:159], v[202:205], v[84:87]
	v_mfma_f32_16x16x32_bf16 v[68:71], v[156:159], v[220:223], v[68:71]
	v_mfma_f32_16x16x32_bf16 v[68:71], v[152:155], v[206:209], v[68:71]
	v_mfma_f32_16x16x32_bf16 v[64:67], v[160:163], v[206:209], v[64:67]
	v_mfma_f32_16x16x32_bf16 v[64:67], v[164:167], v[220:223], v[64:67]
	v_mfma_f32_16x16x32_bf16 v[80:83], v[164:167], v[202:205], v[80:83]
	v_mfma_f32_16x16x32_bf16 v[80:83], v[160:163], v[198:201], v[80:83]
	v_mfma_f32_16x16x32_bf16 v[96:99], v[160:163], v[190:193], v[96:99]
	v_mfma_f32_16x16x32_bf16 v[96:99], v[164:167], v[194:197], v[96:99]
	v_mfma_f32_16x16x32_bf16 v[112:115], v[164:167], v[186:189], v[112:115]
	v_mfma_f32_16x16x32_bf16 v[112:115], v[160:163], v[182:185], v[112:115]
	s_barrier
	s_add_i32 s48, s48, s63
	v_lshl_add_u64 v[226:227], v[134:135], 0, s[10:11]
	s_mov_b32 m0, s48
	s_nop 0
	global_load_lds_dwordx4 v[226:227], off
	v_lshl_add_u64 v[226:227], v[134:135], 0, s[12:13]
	s_add_i32 m0, s48, 0x2000
	s_add_i32 s48, s49, s63
	global_load_lds_dwordx4 v[226:227], off
	v_lshl_add_u64 v[226:227], v[134:135], 0, s[14:15]
	s_mov_b32 m0, s48
	v_lshl_add_u64 v[134:135], v[134:135], 0, s[16:17]
	global_load_lds_dwordx4 v[226:227], off
	s_add_i32 m0, s48, 0x2000
	s_nop 0
	global_load_lds_dwordx4 v[134:135], off
	v_lshl_add_u64 v[134:135], v[224:225], 0, s[10:11]
	s_mov_b32 m0, s68
	s_nop 0
	global_load_lds_dwordx4 v[134:135], off
	v_lshl_add_u64 v[134:135], v[224:225], 0, s[12:13]
	s_mov_b32 m0, s69
	s_nop 0
	global_load_lds_dwordx4 v[134:135], off
	ds_read_b128 v[182:185], v138 offset:49152
	ds_read_b128 v[186:189], v138 offset:50176
	ds_read_b128 v[190:193], v138 offset:51200
	ds_read_b128 v[194:197], v138 offset:52224
	ds_read_b128 v[198:201], v138 offset:53248
	ds_read_b128 v[202:205], v138 offset:54272
	ds_read_b128 v[206:209], v138 offset:55296
	ds_read_b128 v[220:223], v138 offset:56320
	s_waitcnt vmcnt(8)
	s_waitcnt lgkmcnt(0)
	s_barrier
	s_waitcnt lgkmcnt(0)
	v_mfma_f32_16x16x32_bf16 v[60:63], v[130:133], v[182:185], v[60:63]
	v_mfma_f32_16x16x32_bf16 v[60:63], v[140:143], v[186:189], v[60:63]
	v_mfma_f32_16x16x32_bf16 v[44:47], v[140:143], v[194:197], v[44:47]
	v_mfma_f32_16x16x32_bf16 v[44:47], v[130:133], v[190:193], v[44:47]
	v_mfma_f32_16x16x32_bf16 v[28:31], v[130:133], v[198:201], v[28:31]
	v_mfma_f32_16x16x32_bf16 v[28:31], v[140:143], v[202:205], v[28:31]
	v_mfma_f32_16x16x32_bf16 v[12:15], v[140:143], v[220:223], v[12:15]
	v_mfma_f32_16x16x32_bf16 v[12:15], v[130:133], v[206:209], v[12:15]
	v_mfma_f32_16x16x32_bf16 v[8:11], v[144:147], v[206:209], v[8:11]
	v_mfma_f32_16x16x32_bf16 v[8:11], v[148:151], v[220:223], v[8:11]
	v_mfma_f32_16x16x32_bf16 v[24:27], v[148:151], v[202:205], v[24:27]
	v_mfma_f32_16x16x32_bf16 v[24:27], v[144:147], v[198:201], v[24:27]
	v_mfma_f32_16x16x32_bf16 v[40:43], v[144:147], v[190:193], v[40:43]
	v_mfma_f32_16x16x32_bf16 v[40:43], v[148:151], v[194:197], v[40:43]
	v_mfma_f32_16x16x32_bf16 v[56:59], v[148:151], v[186:189], v[56:59]
	v_mfma_f32_16x16x32_bf16 v[56:59], v[144:147], v[182:185], v[56:59]
	v_mfma_f32_16x16x32_bf16 v[52:55], v[152:155], v[182:185], v[52:55]
	v_mfma_f32_16x16x32_bf16 v[52:55], v[156:159], v[186:189], v[52:55]
	v_mfma_f32_16x16x32_bf16 v[36:39], v[156:159], v[194:197], v[36:39]
	v_mfma_f32_16x16x32_bf16 v[36:39], v[152:155], v[190:193], v[36:39]
	v_mfma_f32_16x16x32_bf16 v[20:23], v[152:155], v[198:201], v[20:23]
	v_mfma_f32_16x16x32_bf16 v[20:23], v[156:159], v[202:205], v[20:23]
	v_mfma_f32_16x16x32_bf16 v[4:7], v[156:159], v[220:223], v[4:7]
	v_mfma_f32_16x16x32_bf16 v[4:7], v[152:155], v[206:209], v[4:7]
	v_mfma_f32_16x16x32_bf16 v[0:3], v[160:163], v[206:209], v[0:3]
	v_mfma_f32_16x16x32_bf16 v[0:3], v[164:167], v[220:223], v[0:3]
	v_mfma_f32_16x16x32_bf16 v[16:19], v[164:167], v[202:205], v[16:19]
	v_mfma_f32_16x16x32_bf16 v[16:19], v[160:163], v[198:201], v[16:19]
	v_mfma_f32_16x16x32_bf16 v[32:35], v[160:163], v[190:193], v[32:35]
	v_mfma_f32_16x16x32_bf16 v[32:35], v[164:167], v[194:197], v[32:35]
	v_mfma_f32_16x16x32_bf16 v[48:51], v[164:167], v[186:189], v[48:51]
	v_mfma_f32_16x16x32_bf16 v[48:51], v[160:163], v[182:185], v[48:51]
	s_barrier
	s_cmp_gt_u32 s80, 13
	s_cbranch_scc0 .LBB0_784
	s_and_b64 vcc, exec, s[30:31]
	s_cbranch_vccz .LBB0_787
	s_barrier

.LBB0_856:
	s_add_i32 s78, s78, 2
	s_mov_b32 s50, s78
	s_ashr_i32 s51, s50, 31
	s_lshl_b64 s[80:81], s[50:51], 7
	v_lshl_add_u64 v[224:225], v[130:131], 0, s[80:81]
	v_lshl_add_u64 v[226:227], v[224:225], 0, s[10:11]
	s_add_i32 m0, s62, 0xc000
	s_nop 0
	global_load_lds_dwordx4 v[226:227], off
	v_lshl_add_u64 v[224:225], v[224:225], 0, s[12:13]
	s_add_i32 m0, s62, 0xe000
	s_nop 0
	global_load_lds_dwordx4 v[224:225], off
	s_add_u32 s51, s80, 0x100
	s_addc_u32 s79, s81, 0
	s_add_u32 s82, s30, s51
	s_addc_u32 s83, s31, s79
	s_add_u32 s84, s28, s51
	s_addc_u32 s79, s29, s79
	s_add_i32 s85, 0, 0x10000
	s_cmp_eq_u32 s50, 14
	s_cselect_b32 s51, s39, s83
	s_cselect_b32 s50, s76, s82
	v_add_u32_e32 v135, s85, v133
	s_cselect_b32 s83, s35, s79
	s_cselect_b32 s82, s77, s84
	s_add_i32 s79, 0, 0x14000
	ds_read_b128 v[136:139], v135
	ds_read_b128 v[140:143], v135 offset:1024
	ds_read_b128 v[144:147], v135 offset:2048
	ds_read_b128 v[148:151], v135 offset:3072
	v_add_u32_e32 v135, s79, v133
	ds_read_b128 v[152:155], v135
	ds_read_b128 v[156:159], v135 offset:1024
	ds_read_b128 v[160:163], v135 offset:2048
	ds_read_b128 v[164:167], v135 offset:3072
	ds_read_b128 v[182:185], v134
	ds_read_b128 v[186:189], v134 offset:1024
	ds_read_b128 v[190:193], v134 offset:2048
	ds_read_b128 v[194:197], v134 offset:3072
	ds_read_b128 v[198:201], v134 offset:4096
	ds_read_b128 v[202:205], v134 offset:5120
	ds_read_b128 v[206:209], v134 offset:6144
	ds_read_b128 v[220:223], v134 offset:7168
	s_nop 0
	s_waitcnt vmcnt(8)
	s_waitcnt lgkmcnt(0)
	s_barrier
	s_waitcnt lgkmcnt(0)
	v_mfma_f32_16x16x32_bf16 v[124:127], v[136:139], v[182:185], v[124:127]
	v_mfma_f32_16x16x32_bf16 v[124:127], v[140:143], v[186:189], v[124:127]
	v_mfma_f32_16x16x32_bf16 v[116:119], v[140:143], v[194:197], v[116:119]
	v_mfma_f32_16x16x32_bf16 v[116:119], v[136:139], v[190:193], v[116:119]
	v_mfma_f32_16x16x32_bf16 v[100:103], v[136:139], v[198:201], v[100:103]
	v_mfma_f32_16x16x32_bf16 v[100:103], v[140:143], v[202:205], v[100:103]
	v_mfma_f32_16x16x32_bf16 v[84:87], v[140:143], v[220:223], v[84:87]
	v_mfma_f32_16x16x32_bf16 v[84:87], v[136:139], v[206:209], v[84:87]
	v_mfma_f32_16x16x32_bf16 v[80:83], v[144:147], v[206:209], v[80:83]
	v_mfma_f32_16x16x32_bf16 v[80:83], v[148:151], v[220:223], v[80:83]
	v_mfma_f32_16x16x32_bf16 v[96:99], v[148:151], v[202:205], v[96:99]
	v_mfma_f32_16x16x32_bf16 v[96:99], v[144:147], v[198:201], v[96:99]
	v_mfma_f32_16x16x32_bf16 v[112:115], v[144:147], v[190:193], v[112:115]
	v_mfma_f32_16x16x32_bf16 v[112:115], v[148:151], v[194:197], v[112:115]
	v_mfma_f32_16x16x32_bf16 v[120:123], v[148:151], v[186:189], v[120:123]
	v_mfma_f32_16x16x32_bf16 v[120:123], v[144:147], v[182:185], v[120:123]
	v_mfma_f32_16x16x32_bf16 v[108:111], v[152:155], v[182:185], v[108:111]
	v_mfma_f32_16x16x32_bf16 v[108:111], v[156:159], v[186:189], v[108:111]
	v_mfma_f32_16x16x32_bf16 v[92:95], v[156:159], v[194:197], v[92:95]
	v_mfma_f32_16x16x32_bf16 v[92:95], v[152:155], v[190:193], v[92:95]
	v_mfma_f32_16x16x32_bf16 v[76:79], v[152:155], v[198:201], v[76:79]
	v_mfma_f32_16x16x32_bf16 v[76:79], v[156:159], v[202:205], v[76:79]
	v_mfma_f32_16x16x32_bf16 v[68:71], v[156:159], v[220:223], v[68:71]
	v_mfma_f32_16x16x32_bf16 v[68:71], v[152:155], v[206:209], v[68:71]
	v_mfma_f32_16x16x32_bf16 v[64:67], v[160:163], v[206:209], v[64:67]
	v_mfma_f32_16x16x32_bf16 v[64:67], v[164:167], v[220:223], v[64:67]
	v_mfma_f32_16x16x32_bf16 v[72:75], v[164:167], v[202:205], v[72:75]
	v_mfma_f32_16x16x32_bf16 v[72:75], v[160:163], v[198:201], v[72:75]
	v_mfma_f32_16x16x32_bf16 v[88:91], v[160:163], v[190:193], v[88:91]
	v_mfma_f32_16x16x32_bf16 v[88:91], v[164:167], v[194:197], v[88:91]
	v_mfma_f32_16x16x32_bf16 v[104:107], v[164:167], v[186:189], v[104:107]
	v_mfma_f32_16x16x32_bf16 v[104:107], v[160:163], v[182:185], v[104:107]
	s_barrier
	s_add_i32 s80, s85, s59
	v_lshl_add_u64 v[224:225], s[82:83], 0, v[172:173]
	s_mov_b32 m0, s80
	s_nop 0
	global_load_lds_dwordx4 v[224:225], off
	v_lshl_add_u64 v[226:227], v[224:225], 0, s[40:41]
	s_add_i32 m0, s80, 0x2000
	s_add_i32 s79, s79, s59
	global_load_lds_dwordx4 v[226:227], off
	v_lshl_add_u64 v[226:227], v[224:225], 0, s[4:5]
	s_mov_b32 m0, s79
	s_nop 0
	global_load_lds_dwordx4 v[226:227], off
	v_lshl_add_u64 v[226:227], v[224:225], 0, s[6:7]
	s_add_i32 m0, s79, 0x2000
	s_nop 0
	global_load_lds_dwordx4 v[226:227], off
	v_lshl_add_u64 v[226:227], s[50:51], 0, v[128:129]
	s_mov_b32 m0, s62
	v_lshl_add_u64 v[228:229], v[226:227], 0, s[40:41]
	global_load_lds_dwordx4 v[226:227], off
	s_mov_b32 m0, s63
	s_nop 0
	global_load_lds_dwordx4 v[228:229], off
	ds_read_b128 v[182:185], v134 offset:16384
	ds_read_b128 v[186:189], v134 offset:17408
	ds_read_b128 v[190:193], v134 offset:18432
	ds_read_b128 v[194:197], v134 offset:19456
	ds_read_b128 v[198:201], v134 offset:20480
	ds_read_b128 v[202:205], v134 offset:21504
	ds_read_b128 v[206:209], v134 offset:22528
	ds_read_b128 v[220:223], v134 offset:23552
	s_waitcnt vmcnt(8)
	s_waitcnt lgkmcnt(0)
	s_barrier
	s_waitcnt lgkmcnt(0)
	v_mfma_f32_16x16x32_bf16 v[60:63], v[136:139], v[182:185], v[60:63]
	v_mfma_f32_16x16x32_bf16 v[60:63], v[140:143], v[186:189], v[60:63]
	v_mfma_f32_16x16x32_bf16 v[52:55], v[140:143], v[194:197], v[52:55]
	v_mfma_f32_16x16x32_bf16 v[52:55], v[136:139], v[190:193], v[52:55]
	v_mfma_f32_16x16x32_bf16 v[36:39], v[136:139], v[198:201], v[36:39]
	v_mfma_f32_16x16x32_bf16 v[36:39], v[140:143], v[202:205], v[36:39]
	v_mfma_f32_16x16x32_bf16 v[20:23], v[140:143], v[220:223], v[20:23]
	v_mfma_f32_16x16x32_bf16 v[20:23], v[136:139], v[206:209], v[20:23]
	v_mfma_f32_16x16x32_bf16 v[16:19], v[144:147], v[206:209], v[16:19]
	v_mfma_f32_16x16x32_bf16 v[16:19], v[148:151], v[220:223], v[16:19]
	v_mfma_f32_16x16x32_bf16 v[32:35], v[148:151], v[202:205], v[32:35]
	v_mfma_f32_16x16x32_bf16 v[32:35], v[144:147], v[198:201], v[32:35]
	v_mfma_f32_16x16x32_bf16 v[48:51], v[144:147], v[190:193], v[48:51]
	v_mfma_f32_16x16x32_bf16 v[48:51], v[148:151], v[194:197], v[48:51]
	v_mfma_f32_16x16x32_bf16 v[56:59], v[148:151], v[186:189], v[56:59]
	v_mfma_f32_16x16x32_bf16 v[56:59], v[144:147], v[182:185], v[56:59]
	v_mfma_f32_16x16x32_bf16 v[44:47], v[152:155], v[182:185], v[44:47]
	v_mfma_f32_16x16x32_bf16 v[44:47], v[156:159], v[186:189], v[44:47]
	v_mfma_f32_16x16x32_bf16 v[28:31], v[156:159], v[194:197], v[28:31]
	v_mfma_f32_16x16x32_bf16 v[28:31], v[152:155], v[190:193], v[28:31]
	v_mfma_f32_16x16x32_bf16 v[12:15], v[152:155], v[198:201], v[12:15]
	v_mfma_f32_16x16x32_bf16 v[12:15], v[156:159], v[202:205], v[12:15]
	v_mfma_f32_16x16x32_bf16 v[4:7], v[156:159], v[220:223], v[4:7]
	v_mfma_f32_16x16x32_bf16 v[4:7], v[152:155], v[206:209], v[4:7]
	v_mfma_f32_16x16x32_bf16 v[0:3], v[160:163], v[206:209], v[0:3]
	v_mfma_f32_16x16x32_bf16 v[0:3], v[164:167], v[220:223], v[0:3]
	v_mfma_f32_16x16x32_bf16 v[8:11], v[164:167], v[202:205], v[8:11]
	v_mfma_f32_16x16x32_bf16 v[8:11], v[160:163], v[198:201], v[8:11]
	v_mfma_f32_16x16x32_bf16 v[24:27], v[160:163], v[190:193], v[24:27]
	v_mfma_f32_16x16x32_bf16 v[24:27], v[164:167], v[194:197], v[24:27]
	v_mfma_f32_16x16x32_bf16 v[40:43], v[164:167], v[186:189], v[40:43]
	v_mfma_f32_16x16x32_bf16 v[40:43], v[160:163], v[182:185], v[40:43]
	s_barrier
	s_mov_b32 m0, s68
	v_lshl_add_u64 v[228:229], v[226:227], 0, s[4:5]
	global_load_lds_dwordx4 v[228:229], off
	v_lshl_add_u64 v[228:229], v[226:227], 0, s[6:7]
	s_mov_b32 m0, s69
	s_nop 0
	global_load_lds_dwordx4 v[228:229], off
	s_add_i32 s50, 0, 0x18000
	v_add_u32_e32 v135, s50, v133
	s_add_i32 s51, 0, 0x1c000
	ds_read_b128 v[136:139], v135
	ds_read_b128 v[140:143], v135 offset:1024
	ds_read_b128 v[144:147], v135 offset:2048
	ds_read_b128 v[148:151], v135 offset:3072
	v_add_u32_e32 v135, s51, v133
	ds_read_b128 v[152:155], v135
	ds_read_b128 v[156:159], v135 offset:1024
	ds_read_b128 v[160:163], v135 offset:2048
	ds_read_b128 v[164:167], v135 offset:3072
	ds_read_b128 v[182:185], v134 offset:32768
	ds_read_b128 v[186:189], v134 offset:33792
	ds_read_b128 v[190:193], v134 offset:34816
	ds_read_b128 v[194:197], v134 offset:35840
	ds_read_b128 v[198:201], v134 offset:36864
	ds_read_b128 v[202:205], v134 offset:37888
	ds_read_b128 v[206:209], v134 offset:38912
	ds_read_b128 v[220:223], v134 offset:39936
	s_nop 0
	s_waitcnt vmcnt(8)
	s_waitcnt lgkmcnt(0)
	s_barrier
	s_waitcnt lgkmcnt(0)
	v_mfma_f32_16x16x32_bf16 v[124:127], v[136:139], v[182:185], v[124:127]
	v_mfma_f32_16x16x32_bf16 v[124:127], v[140:143], v[186:189], v[124:127]
	v_mfma_f32_16x16x32_bf16 v[116:119], v[140:143], v[194:197], v[116:119]
	v_mfma_f32_16x16x32_bf16 v[116:119], v[136:139], v[190:193], v[116:119]
	v_mfma_f32_16x16x32_bf16 v[100:103], v[136:139], v[198:201], v[100:103]
	v_mfma_f32_16x16x32_bf16 v[100:103], v[140:143], v[202:205], v[100:103]
	v_mfma_f32_16x16x32_bf16 v[84:87], v[140:143], v[220:223], v[84:87]
	v_mfma_f32_16x16x32_bf16 v[84:87], v[136:139], v[206:209], v[84:87]
	v_mfma_f32_16x16x32_bf16 v[80:83], v[144:147], v[206:209], v[80:83]
	v_mfma_f32_16x16x32_bf16 v[80:83], v[148:151], v[220:223], v[80:83]
	v_mfma_f32_16x16x32_bf16 v[96:99], v[148:151], v[202:205], v[96:99]
	v_mfma_f32_16x16x32_bf16 v[96:99], v[144:147], v[198:201], v[96:99]
	v_mfma_f32_16x16x32_bf16 v[112:115], v[144:147], v[190:193], v[112:115]
	v_mfma_f32_16x16x32_bf16 v[112:115], v[148:151], v[194:197], v[112:115]
	v_mfma_f32_16x16x32_bf16 v[120:123], v[148:151], v[186:189], v[120:123]
	v_mfma_f32_16x16x32_bf16 v[120:123], v[144:147], v[182:185], v[120:123]
	v_mfma_f32_16x16x32_bf16 v[108:111], v[152:155], v[182:185], v[108:111]
	v_mfma_f32_16x16x32_bf16 v[108:111], v[156:159], v[186:189], v[108:111]
	v_mfma_f32_16x16x32_bf16 v[92:95], v[156:159], v[194:197], v[92:95]
	v_mfma_f32_16x16x32_bf16 v[92:95], v[152:155], v[190:193], v[92:95]
	v_mfma_f32_16x16x32_bf16 v[76:79], v[152:155], v[198:201], v[76:79]
	v_mfma_f32_16x16x32_bf16 v[76:79], v[156:159], v[202:205], v[76:79]
	v_mfma_f32_16x16x32_bf16 v[68:71], v[156:159], v[220:223], v[68:71]
	v_mfma_f32_16x16x32_bf16 v[68:71], v[152:155], v[206:209], v[68:71]
	v_mfma_f32_16x16x32_bf16 v[64:67], v[160:163], v[206:209], v[64:67]
	v_mfma_f32_16x16x32_bf16 v[64:67], v[164:167], v[220:223], v[64:67]
	v_mfma_f32_16x16x32_bf16 v[72:75], v[164:167], v[202:205], v[72:75]
	v_mfma_f32_16x16x32_bf16 v[72:75], v[160:163], v[198:201], v[72:75]
	v_mfma_f32_16x16x32_bf16 v[88:91], v[160:163], v[190:193], v[88:91]
	v_mfma_f32_16x16x32_bf16 v[88:91], v[164:167], v[194:197], v[88:91]
	v_mfma_f32_16x16x32_bf16 v[104:107], v[164:167], v[186:189], v[104:107]
	v_mfma_f32_16x16x32_bf16 v[104:107], v[160:163], v[182:185], v[104:107]
	s_barrier
	s_add_i32 s50, s50, s59
	v_lshl_add_u64 v[228:229], v[224:225], 0, s[10:11]
	s_mov_b32 m0, s50
	s_nop 0
	global_load_lds_dwordx4 v[228:229], off
	v_lshl_add_u64 v[228:229], v[224:225], 0, s[12:13]
	s_add_i32 m0, s50, 0x2000
	s_add_i32 s50, s51, s59
	global_load_lds_dwordx4 v[228:229], off
	v_lshl_add_u64 v[228:229], v[224:225], 0, s[14:15]
	s_mov_b32 m0, s50
	v_lshl_add_u64 v[224:225], v[224:225], 0, s[16:17]
	global_load_lds_dwordx4 v[228:229], off
	s_add_i32 m0, s50, 0x2000
	s_nop 0
	global_load_lds_dwordx4 v[224:225], off
	v_lshl_add_u64 v[224:225], v[226:227], 0, s[10:11]
	s_mov_b32 m0, s72
	s_nop 0
	global_load_lds_dwordx4 v[224:225], off
	v_lshl_add_u64 v[224:225], v[226:227], 0, s[12:13]
	s_mov_b32 m0, s73
	s_nop 0
	global_load_lds_dwordx4 v[224:225], off
	ds_read_b128 v[182:185], v134 offset:49152
	ds_read_b128 v[186:189], v134 offset:50176
	ds_read_b128 v[190:193], v134 offset:51200
	ds_read_b128 v[194:197], v134 offset:52224
	ds_read_b128 v[198:201], v134 offset:53248
	ds_read_b128 v[202:205], v134 offset:54272
	ds_read_b128 v[206:209], v134 offset:55296
	ds_read_b128 v[220:223], v134 offset:56320
	s_waitcnt vmcnt(8)
	s_waitcnt lgkmcnt(0)
	s_barrier
	s_waitcnt lgkmcnt(0)
	v_mfma_f32_16x16x32_bf16 v[60:63], v[136:139], v[182:185], v[60:63]
	v_mfma_f32_16x16x32_bf16 v[60:63], v[140:143], v[186:189], v[60:63]
	v_mfma_f32_16x16x32_bf16 v[52:55], v[140:143], v[194:197], v[52:55]
	v_mfma_f32_16x16x32_bf16 v[52:55], v[136:139], v[190:193], v[52:55]
	v_mfma_f32_16x16x32_bf16 v[36:39], v[136:139], v[198:201], v[36:39]
	v_mfma_f32_16x16x32_bf16 v[36:39], v[140:143], v[202:205], v[36:39]
	v_mfma_f32_16x16x32_bf16 v[20:23], v[140:143], v[220:223], v[20:23]
	v_mfma_f32_16x16x32_bf16 v[20:23], v[136:139], v[206:209], v[20:23]
	v_mfma_f32_16x16x32_bf16 v[16:19], v[144:147], v[206:209], v[16:19]
	v_mfma_f32_16x16x32_bf16 v[16:19], v[148:151], v[220:223], v[16:19]
	v_mfma_f32_16x16x32_bf16 v[32:35], v[148:151], v[202:205], v[32:35]
	v_mfma_f32_16x16x32_bf16 v[32:35], v[144:147], v[198:201], v[32:35]
	v_mfma_f32_16x16x32_bf16 v[48:51], v[144:147], v[190:193], v[48:51]
	v_mfma_f32_16x16x32_bf16 v[48:51], v[148:151], v[194:197], v[48:51]
	v_mfma_f32_16x16x32_bf16 v[56:59], v[148:151], v[186:189], v[56:59]
	v_mfma_f32_16x16x32_bf16 v[56:59], v[144:147], v[182:185], v[56:59]
	v_mfma_f32_16x16x32_bf16 v[44:47], v[152:155], v[182:185], v[44:47]
	v_mfma_f32_16x16x32_bf16 v[44:47], v[156:159], v[186:189], v[44:47]
	v_mfma_f32_16x16x32_bf16 v[28:31], v[156:159], v[194:197], v[28:31]
	v_mfma_f32_16x16x32_bf16 v[28:31], v[152:155], v[190:193], v[28:31]
	v_mfma_f32_16x16x32_bf16 v[12:15], v[152:155], v[198:201], v[12:15]
	v_mfma_f32_16x16x32_bf16 v[12:15], v[156:159], v[202:205], v[12:15]
	v_mfma_f32_16x16x32_bf16 v[4:7], v[156:159], v[220:223], v[4:7]
	v_mfma_f32_16x16x32_bf16 v[4:7], v[152:155], v[206:209], v[4:7]
	v_mfma_f32_16x16x32_bf16 v[0:3], v[160:163], v[206:209], v[0:3]
	v_mfma_f32_16x16x32_bf16 v[0:3], v[164:167], v[220:223], v[0:3]
	v_mfma_f32_16x16x32_bf16 v[8:11], v[164:167], v[202:205], v[8:11]
	v_mfma_f32_16x16x32_bf16 v[8:11], v[160:163], v[198:201], v[8:11]
	v_mfma_f32_16x16x32_bf16 v[24:27], v[160:163], v[190:193], v[24:27]
	v_mfma_f32_16x16x32_bf16 v[24:27], v[164:167], v[194:197], v[24:27]
	v_mfma_f32_16x16x32_bf16 v[40:43], v[164:167], v[186:189], v[40:43]
	v_mfma_f32_16x16x32_bf16 v[40:43], v[160:163], v[182:185], v[40:43]
	s_barrier
	s_cmp_gt_u32 s78, 13
	s_cbranch_scc0 .LBB0_856
	s_and_b64 vcc, exec, s[8:9]
	s_cbranch_vccz .LBB0_859
	s_barrier

.LBB0_970:
	s_add_i32 s21, s21, 2
	s_mov_b32 s38, s21
	s_ashr_i32 s39, s38, 31
	s_lshl_b64 s[74:75], s[38:39], 7
	s_add_u32 s39, s74, 0x100
	s_addc_u32 s73, s75, 0
	s_add_u32 s76, s34, s39
	s_addc_u32 s77, s35, s73
	s_add_u32 s78, s30, s39
	s_addc_u32 s73, s31, s73
	s_cmp_eq_u32 s38, 14
	s_cselect_b32 s39, s67, s77
	s_cselect_b32 s38, s68, s76
	s_cselect_b32 s77, s23, s73
	s_cselect_b32 s76, s66, s78
	s_add_u32 s74, s34, s74
	s_addc_u32 s75, s35, s75
	v_lshl_add_u64 v[208:209], s[74:75], 0, v[130:131]
	s_mov_b32 m0, s59
	v_lshl_add_u64 v[216:217], v[208:209], 0, s[14:15]
	global_load_lds_dwordx4 v[216:217], off
	v_lshl_add_u64 v[208:209], v[208:209], 0, s[16:17]
	s_mov_b32 m0, s60
	s_nop 0
	global_load_lds_dwordx4 v[208:209], off
	ds_read_b128 v[144:147], v140
	ds_read_b128 v[148:151], v140 offset:1024
	ds_read_b128 v[152:155], v140 offset:2048
	ds_read_b128 v[156:159], v140 offset:3072
	ds_read_b128 v[160:163], v141
	ds_read_b128 v[164:167], v141 offset:1024
	ds_read_b128 v[172:175], v141 offset:2048
	ds_read_b128 v[176:179], v141 offset:3072
	ds_read_b128 v[180:183], v142
	ds_read_b128 v[184:187], v142 offset:1024
	ds_read_b128 v[188:191], v142 offset:2048
	ds_read_b128 v[192:195], v142 offset:3072
	ds_read_b128 v[196:199], v142 offset:4096
	ds_read_b128 v[200:203], v142 offset:5120
	ds_read_b128 v[204:207], v142 offset:6144
	ds_read_b128 v[212:215], v142 offset:7168
	s_waitcnt vmcnt(8)
	s_waitcnt lgkmcnt(0)
	s_barrier
	s_waitcnt lgkmcnt(0)
	v_mfma_f32_16x16x32_bf16 v[124:127], v[144:147], v[180:183], v[124:127]
	v_mfma_f32_16x16x32_bf16 v[124:127], v[148:151], v[184:187], v[124:127]
	v_mfma_f32_16x16x32_bf16 v[108:111], v[148:151], v[192:195], v[108:111]
	v_mfma_f32_16x16x32_bf16 v[108:111], v[144:147], v[188:191], v[108:111]
	v_mfma_f32_16x16x32_bf16 v[92:95], v[144:147], v[196:199], v[92:95]
	v_mfma_f32_16x16x32_bf16 v[92:95], v[148:151], v[200:203], v[92:95]
	v_mfma_f32_16x16x32_bf16 v[76:79], v[148:151], v[212:215], v[76:79]
	v_mfma_f32_16x16x32_bf16 v[76:79], v[144:147], v[204:207], v[76:79]
	v_mfma_f32_16x16x32_bf16 v[64:67], v[152:155], v[204:207], v[64:67]
	v_mfma_f32_16x16x32_bf16 v[64:67], v[156:159], v[212:215], v[64:67]
	v_mfma_f32_16x16x32_bf16 v[80:83], v[156:159], v[200:203], v[80:83]
	v_mfma_f32_16x16x32_bf16 v[80:83], v[152:155], v[196:199], v[80:83]
	v_mfma_f32_16x16x32_bf16 v[96:99], v[152:155], v[188:191], v[96:99]
	v_mfma_f32_16x16x32_bf16 v[96:99], v[156:159], v[192:195], v[96:99]
	v_mfma_f32_16x16x32_bf16 v[112:115], v[156:159], v[184:187], v[112:115]
	v_mfma_f32_16x16x32_bf16 v[112:115], v[152:155], v[180:183], v[112:115]
	v_mfma_f32_16x16x32_bf16 v[120:123], v[160:163], v[180:183], v[120:123]
	v_mfma_f32_16x16x32_bf16 v[120:123], v[164:167], v[184:187], v[120:123]
	v_mfma_f32_16x16x32_bf16 v[104:107], v[164:167], v[192:195], v[104:107]
	v_mfma_f32_16x16x32_bf16 v[104:107], v[160:163], v[188:191], v[104:107]
	v_mfma_f32_16x16x32_bf16 v[88:91], v[160:163], v[196:199], v[88:91]
	v_mfma_f32_16x16x32_bf16 v[88:91], v[164:167], v[200:203], v[88:91]
	v_mfma_f32_16x16x32_bf16 v[72:75], v[164:167], v[212:215], v[72:75]
	v_mfma_f32_16x16x32_bf16 v[72:75], v[160:163], v[204:207], v[72:75]
	v_mfma_f32_16x16x32_bf16 v[68:71], v[172:175], v[204:207], v[68:71]
	v_mfma_f32_16x16x32_bf16 v[68:71], v[176:179], v[212:215], v[68:71]
	v_mfma_f32_16x16x32_bf16 v[84:87], v[176:179], v[200:203], v[84:87]
	v_mfma_f32_16x16x32_bf16 v[84:87], v[172:175], v[196:199], v[84:87]
	v_mfma_f32_16x16x32_bf16 v[100:103], v[172:175], v[188:191], v[100:103]
	v_mfma_f32_16x16x32_bf16 v[100:103], v[176:179], v[192:195], v[100:103]
	v_mfma_f32_16x16x32_bf16 v[116:119], v[176:179], v[184:187], v[116:119]
	v_mfma_f32_16x16x32_bf16 v[116:119], v[172:175], v[180:183], v[116:119]
	s_barrier
	s_mov_b32 m0, s61
	v_lshl_add_u64 v[208:209], s[76:77], 0, v[128:129]
	global_load_lds_dwordx4 v[208:209], off
	v_lshl_add_u64 v[216:217], v[208:209], 0, s[0:1]
	s_mov_b32 m0, s62
	s_nop 0
	global_load_lds_dwordx4 v[216:217], off
	v_lshl_add_u64 v[216:217], v[208:209], 0, s[2:3]
	s_mov_b32 m0, s63
	s_nop 0
	global_load_lds_dwordx4 v[216:217], off
	v_lshl_add_u64 v[216:217], v[208:209], 0, s[4:5]
	s_mov_b32 m0, s64
	s_nop 0
	global_load_lds_dwordx4 v[216:217], off
	v_lshl_add_u64 v[216:217], s[38:39], 0, v[130:131]
	s_mov_b32 m0, s48
	v_lshl_add_u64 v[218:219], v[216:217], 0, s[0:1]
	global_load_lds_dwordx4 v[216:217], off
	s_mov_b32 m0, s49
	s_nop 0
	global_load_lds_dwordx4 v[218:219], off
	ds_read_b128 v[180:183], v142 offset:16384
	ds_read_b128 v[184:187], v142 offset:17408
	ds_read_b128 v[188:191], v142 offset:18432
	ds_read_b128 v[192:195], v142 offset:19456
	ds_read_b128 v[196:199], v142 offset:20480
	ds_read_b128 v[200:203], v142 offset:21504
	ds_read_b128 v[204:207], v142 offset:22528
	ds_read_b128 v[212:215], v142 offset:23552
	s_waitcnt vmcnt(8)
	s_waitcnt lgkmcnt(0)
	s_barrier
	s_waitcnt lgkmcnt(0)
	v_mfma_f32_16x16x32_bf16 v[60:63], v[144:147], v[180:183], v[60:63]
	v_mfma_f32_16x16x32_bf16 v[60:63], v[148:151], v[184:187], v[60:63]
	v_mfma_f32_16x16x32_bf16 v[44:47], v[148:151], v[192:195], v[44:47]
	v_mfma_f32_16x16x32_bf16 v[44:47], v[144:147], v[188:191], v[44:47]
	v_mfma_f32_16x16x32_bf16 v[28:31], v[144:147], v[196:199], v[28:31]
	v_mfma_f32_16x16x32_bf16 v[28:31], v[148:151], v[200:203], v[28:31]
	v_mfma_f32_16x16x32_bf16 v[12:15], v[148:151], v[212:215], v[12:15]
	v_mfma_f32_16x16x32_bf16 v[12:15], v[144:147], v[204:207], v[12:15]
	v_mfma_f32_16x16x32_bf16 v[0:3], v[152:155], v[204:207], v[0:3]
	v_mfma_f32_16x16x32_bf16 v[0:3], v[156:159], v[212:215], v[0:3]
	v_mfma_f32_16x16x32_bf16 v[16:19], v[156:159], v[200:203], v[16:19]
	v_mfma_f32_16x16x32_bf16 v[16:19], v[152:155], v[196:199], v[16:19]
	v_mfma_f32_16x16x32_bf16 v[32:35], v[152:155], v[188:191], v[32:35]
	v_mfma_f32_16x16x32_bf16 v[32:35], v[156:159], v[192:195], v[32:35]
	v_mfma_f32_16x16x32_bf16 v[48:51], v[156:159], v[184:187], v[48:51]
	v_mfma_f32_16x16x32_bf16 v[48:51], v[152:155], v[180:183], v[48:51]
	v_mfma_f32_16x16x32_bf16 v[56:59], v[160:163], v[180:183], v[56:59]
	v_mfma_f32_16x16x32_bf16 v[56:59], v[164:167], v[184:187], v[56:59]
	v_mfma_f32_16x16x32_bf16 v[40:43], v[164:167], v[192:195], v[40:43]
	v_mfma_f32_16x16x32_bf16 v[40:43], v[160:163], v[188:191], v[40:43]
	v_mfma_f32_16x16x32_bf16 v[24:27], v[160:163], v[196:199], v[24:27]
	v_mfma_f32_16x16x32_bf16 v[24:27], v[164:167], v[200:203], v[24:27]
	v_mfma_f32_16x16x32_bf16 v[8:11], v[164:167], v[212:215], v[8:11]
	v_mfma_f32_16x16x32_bf16 v[8:11], v[160:163], v[204:207], v[8:11]
	v_mfma_f32_16x16x32_bf16 v[4:7], v[172:175], v[204:207], v[4:7]
	v_mfma_f32_16x16x32_bf16 v[4:7], v[176:179], v[212:215], v[4:7]
	v_mfma_f32_16x16x32_bf16 v[20:23], v[176:179], v[200:203], v[20:23]
	v_mfma_f32_16x16x32_bf16 v[20:23], v[172:175], v[196:199], v[20:23]
	v_mfma_f32_16x16x32_bf16 v[36:39], v[172:175], v[188:191], v[36:39]
	v_mfma_f32_16x16x32_bf16 v[36:39], v[176:179], v[192:195], v[36:39]
	v_mfma_f32_16x16x32_bf16 v[52:55], v[176:179], v[184:187], v[52:55]
	v_mfma_f32_16x16x32_bf16 v[52:55], v[172:175], v[180:183], v[52:55]
	s_barrier
	s_mov_b32 m0, s50
	v_lshl_add_u64 v[218:219], v[216:217], 0, s[2:3]
	global_load_lds_dwordx4 v[218:219], off
	v_lshl_add_u64 v[218:219], v[216:217], 0, s[4:5]
	s_mov_b32 m0, s51
	s_nop 0
	global_load_lds_dwordx4 v[218:219], off
	ds_read_b128 v[144:147], v143
	ds_read_b128 v[148:151], v143 offset:1024
	ds_read_b128 v[152:155], v143 offset:2048
	ds_read_b128 v[156:159], v143 offset:3072
	ds_read_b128 v[160:163], v136
	ds_read_b128 v[164:167], v136 offset:1024
	ds_read_b128 v[172:175], v136 offset:2048
	ds_read_b128 v[176:179], v136 offset:3072
	ds_read_b128 v[180:183], v142 offset:32768
	ds_read_b128 v[184:187], v142 offset:33792
	ds_read_b128 v[188:191], v142 offset:34816
	ds_read_b128 v[192:195], v142 offset:35840
	ds_read_b128 v[196:199], v142 offset:36864
	ds_read_b128 v[200:203], v142 offset:37888
	ds_read_b128 v[204:207], v142 offset:38912
	ds_read_b128 v[212:215], v142 offset:39936
	s_waitcnt vmcnt(8)
	s_waitcnt lgkmcnt(0)
	s_barrier
	s_waitcnt lgkmcnt(0)
	v_mfma_f32_16x16x32_bf16 v[124:127], v[144:147], v[180:183], v[124:127]
	v_mfma_f32_16x16x32_bf16 v[124:127], v[148:151], v[184:187], v[124:127]
	v_mfma_f32_16x16x32_bf16 v[108:111], v[148:151], v[192:195], v[108:111]
	v_mfma_f32_16x16x32_bf16 v[108:111], v[144:147], v[188:191], v[108:111]
	v_mfma_f32_16x16x32_bf16 v[92:95], v[144:147], v[196:199], v[92:95]
	v_mfma_f32_16x16x32_bf16 v[92:95], v[148:151], v[200:203], v[92:95]
	v_mfma_f32_16x16x32_bf16 v[76:79], v[148:151], v[212:215], v[76:79]
	v_mfma_f32_16x16x32_bf16 v[76:79], v[144:147], v[204:207], v[76:79]
	v_mfma_f32_16x16x32_bf16 v[64:67], v[152:155], v[204:207], v[64:67]
	v_mfma_f32_16x16x32_bf16 v[64:67], v[156:159], v[212:215], v[64:67]
	v_mfma_f32_16x16x32_bf16 v[80:83], v[156:159], v[200:203], v[80:83]
	v_mfma_f32_16x16x32_bf16 v[80:83], v[152:155], v[196:199], v[80:83]
	v_mfma_f32_16x16x32_bf16 v[96:99], v[152:155], v[188:191], v[96:99]
	v_mfma_f32_16x16x32_bf16 v[96:99], v[156:159], v[192:195], v[96:99]
	v_mfma_f32_16x16x32_bf16 v[112:115], v[156:159], v[184:187], v[112:115]
	v_mfma_f32_16x16x32_bf16 v[112:115], v[152:155], v[180:183], v[112:115]
	v_mfma_f32_16x16x32_bf16 v[120:123], v[160:163], v[180:183], v[120:123]
	v_mfma_f32_16x16x32_bf16 v[120:123], v[164:167], v[184:187], v[120:123]
	v_mfma_f32_16x16x32_bf16 v[104:107], v[164:167], v[192:195], v[104:107]
	v_mfma_f32_16x16x32_bf16 v[104:107], v[160:163], v[188:191], v[104:107]
	v_mfma_f32_16x16x32_bf16 v[88:91], v[160:163], v[196:199], v[88:91]
	v_mfma_f32_16x16x32_bf16 v[88:91], v[164:167], v[200:203], v[88:91]
	v_mfma_f32_16x16x32_bf16 v[72:75], v[164:167], v[212:215], v[72:75]
	v_mfma_f32_16x16x32_bf16 v[72:75], v[160:163], v[204:207], v[72:75]
	v_mfma_f32_16x16x32_bf16 v[68:71], v[172:175], v[204:207], v[68:71]
	v_mfma_f32_16x16x32_bf16 v[68:71], v[176:179], v[212:215], v[68:71]
	v_mfma_f32_16x16x32_bf16 v[84:87], v[176:179], v[200:203], v[84:87]
	v_mfma_f32_16x16x32_bf16 v[84:87], v[172:175], v[196:199], v[84:87]
	v_mfma_f32_16x16x32_bf16 v[100:103], v[172:175], v[188:191], v[100:103]
	v_mfma_f32_16x16x32_bf16 v[100:103], v[176:179], v[192:195], v[100:103]
	v_mfma_f32_16x16x32_bf16 v[116:119], v[176:179], v[184:187], v[116:119]
	v_mfma_f32_16x16x32_bf16 v[116:119], v[172:175], v[180:183], v[116:119]
	s_barrier
	s_mov_b32 m0, s69
	v_lshl_add_u64 v[218:219], v[208:209], 0, s[10:11]
	global_load_lds_dwordx4 v[218:219], off
	v_lshl_add_u64 v[218:219], v[208:209], 0, s[12:13]
	s_mov_b32 m0, s70
	s_nop 0
	global_load_lds_dwordx4 v[218:219], off
	v_lshl_add_u64 v[218:219], v[208:209], 0, s[14:15]
	s_mov_b32 m0, s71
	v_lshl_add_u64 v[208:209], v[208:209], 0, s[16:17]
	global_load_lds_dwordx4 v[218:219], off
	s_mov_b32 m0, s72
	s_nop 0
	global_load_lds_dwordx4 v[208:209], off
	v_lshl_add_u64 v[208:209], v[216:217], 0, s[10:11]
	s_mov_b32 m0, s53
	s_nop 0
	global_load_lds_dwordx4 v[208:209], off
	v_lshl_add_u64 v[208:209], v[216:217], 0, s[12:13]
	s_mov_b32 m0, s54
	s_nop 0
	global_load_lds_dwordx4 v[208:209], off
	ds_read_b128 v[180:183], v142 offset:49152
	ds_read_b128 v[184:187], v142 offset:50176
	ds_read_b128 v[188:191], v142 offset:51200
	ds_read_b128 v[192:195], v142 offset:52224
	ds_read_b128 v[196:199], v142 offset:53248
	ds_read_b128 v[200:203], v142 offset:54272
	ds_read_b128 v[204:207], v142 offset:55296
	ds_read_b128 v[212:215], v142 offset:56320
	s_waitcnt vmcnt(8)
	s_waitcnt lgkmcnt(0)
	s_barrier
	s_waitcnt lgkmcnt(0)
	v_mfma_f32_16x16x32_bf16 v[60:63], v[144:147], v[180:183], v[60:63]
	v_mfma_f32_16x16x32_bf16 v[60:63], v[148:151], v[184:187], v[60:63]
	v_mfma_f32_16x16x32_bf16 v[44:47], v[148:151], v[192:195], v[44:47]
	v_mfma_f32_16x16x32_bf16 v[44:47], v[144:147], v[188:191], v[44:47]
	v_mfma_f32_16x16x32_bf16 v[28:31], v[144:147], v[196:199], v[28:31]
	v_mfma_f32_16x16x32_bf16 v[28:31], v[148:151], v[200:203], v[28:31]
	v_mfma_f32_16x16x32_bf16 v[12:15], v[148:151], v[212:215], v[12:15]
	v_mfma_f32_16x16x32_bf16 v[12:15], v[144:147], v[204:207], v[12:15]
	v_mfma_f32_16x16x32_bf16 v[0:3], v[152:155], v[204:207], v[0:3]
	v_mfma_f32_16x16x32_bf16 v[0:3], v[156:159], v[212:215], v[0:3]
	v_mfma_f32_16x16x32_bf16 v[16:19], v[156:159], v[200:203], v[16:19]
	v_mfma_f32_16x16x32_bf16 v[16:19], v[152:155], v[196:199], v[16:19]
	v_mfma_f32_16x16x32_bf16 v[32:35], v[152:155], v[188:191], v[32:35]
	v_mfma_f32_16x16x32_bf16 v[32:35], v[156:159], v[192:195], v[32:35]
	v_mfma_f32_16x16x32_bf16 v[48:51], v[156:159], v[184:187], v[48:51]
	v_mfma_f32_16x16x32_bf16 v[48:51], v[152:155], v[180:183], v[48:51]
	v_mfma_f32_16x16x32_bf16 v[56:59], v[160:163], v[180:183], v[56:59]
	v_mfma_f32_16x16x32_bf16 v[56:59], v[164:167], v[184:187], v[56:59]
	v_mfma_f32_16x16x32_bf16 v[40:43], v[164:167], v[192:195], v[40:43]
	v_mfma_f32_16x16x32_bf16 v[40:43], v[160:163], v[188:191], v[40:43]
	v_mfma_f32_16x16x32_bf16 v[24:27], v[160:163], v[196:199], v[24:27]
	v_mfma_f32_16x16x32_bf16 v[24:27], v[164:167], v[200:203], v[24:27]
	v_mfma_f32_16x16x32_bf16 v[8:11], v[164:167], v[212:215], v[8:11]
	v_mfma_f32_16x16x32_bf16 v[8:11], v[160:163], v[204:207], v[8:11]
	v_mfma_f32_16x16x32_bf16 v[4:7], v[172:175], v[204:207], v[4:7]
	v_mfma_f32_16x16x32_bf16 v[4:7], v[176:179], v[212:215], v[4:7]
	v_mfma_f32_16x16x32_bf16 v[20:23], v[176:179], v[200:203], v[20:23]
	v_mfma_f32_16x16x32_bf16 v[20:23], v[172:175], v[196:199], v[20:23]
	v_mfma_f32_16x16x32_bf16 v[36:39], v[172:175], v[188:191], v[36:39]
	v_mfma_f32_16x16x32_bf16 v[36:39], v[176:179], v[192:195], v[36:39]
	v_mfma_f32_16x16x32_bf16 v[52:55], v[176:179], v[184:187], v[52:55]
	v_mfma_f32_16x16x32_bf16 v[52:55], v[172:175], v[180:183], v[52:55]
	s_barrier
	s_cmp_gt_u32 s21, 13
	s_cbranch_scc0 .LBB0_970
	s_and_b64 vcc, exec, s[18:19]
	s_cbranch_vccz .LBB0_973
	s_barrier

.LBB0_1046:
	s_add_i32 s55, s55, 2
	s_mov_b32 s56, s55
	s_ashr_i32 s57, s56, 31
	s_lshl_b64 s[58:59], s[56:57], 7
	s_add_u32 s57, s58, 0x100
	s_addc_u32 s60, s59, 0
	s_add_u32 s61, s24, s57
	s_addc_u32 s62, s25, s60
	s_add_u32 s63, s22, s57
	s_addc_u32 s60, s23, s60
	s_cmp_eq_u32 s56, 42
	s_cselect_b32 s57, s1, s62
	s_cselect_b32 s56, s0, s61
	s_cselect_b32 s61, s27, s60
	s_cselect_b32 s60, s26, s63
	v_lshl_add_u64 v[208:209], v[136:137], 0, s[58:59]
	v_lshl_add_u64 v[216:217], v[208:209], 0, s[12:13]
	s_add_i32 m0, s39, 0xc000
	s_nop 0
	global_load_lds_dwordx4 v[216:217], off
	v_lshl_add_u64 v[208:209], v[208:209], 0, s[14:15]
	s_add_i32 m0, s39, 0xe000
	s_nop 0
	global_load_lds_dwordx4 v[208:209], off
	ds_read_b128 v[144:147], v140
	ds_read_b128 v[148:151], v140 offset:1024
	ds_read_b128 v[152:155], v140 offset:2048
	ds_read_b128 v[156:159], v140 offset:3072
	ds_read_b128 v[160:163], v141
	ds_read_b128 v[164:167], v141 offset:1024
	ds_read_b128 v[172:175], v141 offset:2048
	ds_read_b128 v[176:179], v141 offset:3072
	ds_read_b128 v[180:183], v142
	ds_read_b128 v[184:187], v142 offset:1024
	ds_read_b128 v[188:191], v142 offset:2048
	ds_read_b128 v[192:195], v142 offset:3072
	ds_read_b128 v[196:199], v142 offset:4096
	ds_read_b128 v[200:203], v142 offset:5120
	ds_read_b128 v[204:207], v142 offset:6144
	ds_read_b128 v[212:215], v142 offset:7168
	s_waitcnt vmcnt(8)
	s_waitcnt lgkmcnt(0)
	s_barrier
	s_waitcnt lgkmcnt(0)
	v_mfma_f32_16x16x32_bf16 v[124:127], v[144:147], v[180:183], v[124:127]
	v_mfma_f32_16x16x32_bf16 v[124:127], v[148:151], v[184:187], v[124:127]
	v_mfma_f32_16x16x32_bf16 v[116:119], v[148:151], v[192:195], v[116:119]
	v_mfma_f32_16x16x32_bf16 v[116:119], v[144:147], v[188:191], v[116:119]
	v_mfma_f32_16x16x32_bf16 v[100:103], v[144:147], v[196:199], v[100:103]
	v_mfma_f32_16x16x32_bf16 v[100:103], v[148:151], v[200:203], v[100:103]
	v_mfma_f32_16x16x32_bf16 v[84:87], v[148:151], v[212:215], v[84:87]
	v_mfma_f32_16x16x32_bf16 v[84:87], v[144:147], v[204:207], v[84:87]
	v_mfma_f32_16x16x32_bf16 v[80:83], v[152:155], v[204:207], v[80:83]
	v_mfma_f32_16x16x32_bf16 v[80:83], v[156:159], v[212:215], v[80:83]
	v_mfma_f32_16x16x32_bf16 v[96:99], v[156:159], v[200:203], v[96:99]
	v_mfma_f32_16x16x32_bf16 v[96:99], v[152:155], v[196:199], v[96:99]
	v_mfma_f32_16x16x32_bf16 v[112:115], v[152:155], v[188:191], v[112:115]
	v_mfma_f32_16x16x32_bf16 v[112:115], v[156:159], v[192:195], v[112:115]
	v_mfma_f32_16x16x32_bf16 v[120:123], v[156:159], v[184:187], v[120:123]
	v_mfma_f32_16x16x32_bf16 v[120:123], v[152:155], v[180:183], v[120:123]
	v_mfma_f32_16x16x32_bf16 v[108:111], v[160:163], v[180:183], v[108:111]
	v_mfma_f32_16x16x32_bf16 v[108:111], v[164:167], v[184:187], v[108:111]
	v_mfma_f32_16x16x32_bf16 v[92:95], v[164:167], v[192:195], v[92:95]
	v_mfma_f32_16x16x32_bf16 v[92:95], v[160:163], v[188:191], v[92:95]
	v_mfma_f32_16x16x32_bf16 v[76:79], v[160:163], v[196:199], v[76:79]
	v_mfma_f32_16x16x32_bf16 v[76:79], v[164:167], v[200:203], v[76:79]
	v_mfma_f32_16x16x32_bf16 v[68:71], v[164:167], v[212:215], v[68:71]
	v_mfma_f32_16x16x32_bf16 v[68:71], v[160:163], v[204:207], v[68:71]
	v_mfma_f32_16x16x32_bf16 v[64:67], v[172:175], v[204:207], v[64:67]
	v_mfma_f32_16x16x32_bf16 v[64:67], v[176:179], v[212:215], v[64:67]
	v_mfma_f32_16x16x32_bf16 v[72:75], v[176:179], v[200:203], v[72:75]
	v_mfma_f32_16x16x32_bf16 v[72:75], v[172:175], v[196:199], v[72:75]
	v_mfma_f32_16x16x32_bf16 v[88:91], v[172:175], v[188:191], v[88:91]
	v_mfma_f32_16x16x32_bf16 v[88:91], v[176:179], v[192:195], v[88:91]
	v_mfma_f32_16x16x32_bf16 v[104:107], v[176:179], v[184:187], v[104:107]
	v_mfma_f32_16x16x32_bf16 v[104:107], v[172:175], v[180:183], v[104:107]
	s_barrier
	s_add_i32 s58, s49, s38
	v_lshl_add_u64 v[208:209], s[60:61], 0, v[130:131]
	s_mov_b32 m0, s58
	s_nop 0
	global_load_lds_dwordx4 v[208:209], off
	v_lshl_add_u64 v[216:217], v[208:209], 0, s[2:3]
	s_add_i32 m0, s58, 0x2000
	s_add_i32 s58, s50, s38
	global_load_lds_dwordx4 v[216:217], off
	v_lshl_add_u64 v[216:217], v[208:209], 0, s[4:5]
	s_mov_b32 m0, s58
	s_nop 0
	global_load_lds_dwordx4 v[216:217], off
	v_lshl_add_u64 v[216:217], v[208:209], 0, s[6:7]
	s_add_i32 m0, s58, 0x2000
	s_nop 0
	global_load_lds_dwordx4 v[216:217], off
	v_lshl_add_u64 v[216:217], s[56:57], 0, v[128:129]
	s_mov_b32 m0, s39
	v_lshl_add_u64 v[218:219], v[216:217], 0, s[2:3]
	global_load_lds_dwordx4 v[216:217], off
	s_mov_b32 m0, s40
	s_nop 0
	global_load_lds_dwordx4 v[218:219], off
	ds_read_b128 v[180:183], v142 offset:16384
	ds_read_b128 v[184:187], v142 offset:17408
	ds_read_b128 v[188:191], v142 offset:18432
	ds_read_b128 v[192:195], v142 offset:19456
	ds_read_b128 v[196:199], v142 offset:20480
	ds_read_b128 v[200:203], v142 offset:21504
	ds_read_b128 v[204:207], v142 offset:22528
	ds_read_b128 v[212:215], v142 offset:23552
	s_waitcnt vmcnt(8)
	s_waitcnt lgkmcnt(0)
	s_barrier
	s_waitcnt lgkmcnt(0)
	v_mfma_f32_16x16x32_bf16 v[60:63], v[144:147], v[180:183], v[60:63]
	v_mfma_f32_16x16x32_bf16 v[60:63], v[148:151], v[184:187], v[60:63]
	v_mfma_f32_16x16x32_bf16 v[52:55], v[148:151], v[192:195], v[52:55]
	v_mfma_f32_16x16x32_bf16 v[52:55], v[144:147], v[188:191], v[52:55]
	v_mfma_f32_16x16x32_bf16 v[36:39], v[144:147], v[196:199], v[36:39]
	v_mfma_f32_16x16x32_bf16 v[36:39], v[148:151], v[200:203], v[36:39]
	v_mfma_f32_16x16x32_bf16 v[20:23], v[148:151], v[212:215], v[20:23]
	v_mfma_f32_16x16x32_bf16 v[20:23], v[144:147], v[204:207], v[20:23]
	v_mfma_f32_16x16x32_bf16 v[16:19], v[152:155], v[204:207], v[16:19]
	v_mfma_f32_16x16x32_bf16 v[16:19], v[156:159], v[212:215], v[16:19]
	v_mfma_f32_16x16x32_bf16 v[32:35], v[156:159], v[200:203], v[32:35]
	v_mfma_f32_16x16x32_bf16 v[32:35], v[152:155], v[196:199], v[32:35]
	v_mfma_f32_16x16x32_bf16 v[48:51], v[152:155], v[188:191], v[48:51]
	v_mfma_f32_16x16x32_bf16 v[48:51], v[156:159], v[192:195], v[48:51]
	v_mfma_f32_16x16x32_bf16 v[56:59], v[156:159], v[184:187], v[56:59]
	v_mfma_f32_16x16x32_bf16 v[56:59], v[152:155], v[180:183], v[56:59]
	v_mfma_f32_16x16x32_bf16 v[44:47], v[160:163], v[180:183], v[44:47]
	v_mfma_f32_16x16x32_bf16 v[44:47], v[164:167], v[184:187], v[44:47]
	v_mfma_f32_16x16x32_bf16 v[28:31], v[164:167], v[192:195], v[28:31]
	v_mfma_f32_16x16x32_bf16 v[28:31], v[160:163], v[188:191], v[28:31]
	v_mfma_f32_16x16x32_bf16 v[12:15], v[160:163], v[196:199], v[12:15]
	v_mfma_f32_16x16x32_bf16 v[12:15], v[164:167], v[200:203], v[12:15]
	v_mfma_f32_16x16x32_bf16 v[4:7], v[164:167], v[212:215], v[4:7]
	v_mfma_f32_16x16x32_bf16 v[4:7], v[160:163], v[204:207], v[4:7]
	v_mfma_f32_16x16x32_bf16 v[0:3], v[172:175], v[204:207], v[0:3]
	v_mfma_f32_16x16x32_bf16 v[0:3], v[176:179], v[212:215], v[0:3]
	v_mfma_f32_16x16x32_bf16 v[8:11], v[176:179], v[200:203], v[8:11]
	v_mfma_f32_16x16x32_bf16 v[8:11], v[172:175], v[196:199], v[8:11]
	v_mfma_f32_16x16x32_bf16 v[24:27], v[172:175], v[188:191], v[24:27]
	v_mfma_f32_16x16x32_bf16 v[24:27], v[176:179], v[192:195], v[24:27]
	v_mfma_f32_16x16x32_bf16 v[40:43], v[176:179], v[184:187], v[40:43]
	v_mfma_f32_16x16x32_bf16 v[40:43], v[172:175], v[180:183], v[40:43]
	s_barrier
	s_mov_b32 m0, s41
	v_lshl_add_u64 v[218:219], v[216:217], 0, s[4:5]
	global_load_lds_dwordx4 v[218:219], off
	v_lshl_add_u64 v[218:219], v[216:217], 0, s[6:7]
	s_mov_b32 m0, s42
	s_nop 0
	global_load_lds_dwordx4 v[218:219], off
	s_add_i32 s56, 0, 0x18000
	v_add_u32_e32 v143, s56, v139
	s_add_i32 s57, 0, 0x1c000
	ds_read_b128 v[144:147], v143
	ds_read_b128 v[148:151], v143 offset:1024
	ds_read_b128 v[152:155], v143 offset:2048
	ds_read_b128 v[156:159], v143 offset:3072
	v_add_u32_e32 v143, s57, v139
	ds_read_b128 v[160:163], v143
	ds_read_b128 v[164:167], v143 offset:1024
	ds_read_b128 v[172:175], v143 offset:2048
	ds_read_b128 v[176:179], v143 offset:3072
	ds_read_b128 v[180:183], v142 offset:32768
	ds_read_b128 v[184:187], v142 offset:33792
	ds_read_b128 v[188:191], v142 offset:34816
	ds_read_b128 v[192:195], v142 offset:35840
	ds_read_b128 v[196:199], v142 offset:36864
	ds_read_b128 v[200:203], v142 offset:37888
	ds_read_b128 v[204:207], v142 offset:38912
	ds_read_b128 v[212:215], v142 offset:39936
	s_nop 0
	s_waitcnt vmcnt(8)
	s_waitcnt lgkmcnt(0)
	s_barrier
	s_waitcnt lgkmcnt(0)
	v_mfma_f32_16x16x32_bf16 v[124:127], v[144:147], v[180:183], v[124:127]
	v_mfma_f32_16x16x32_bf16 v[124:127], v[148:151], v[184:187], v[124:127]
	v_mfma_f32_16x16x32_bf16 v[116:119], v[148:151], v[192:195], v[116:119]
	v_mfma_f32_16x16x32_bf16 v[116:119], v[144:147], v[188:191], v[116:119]
	v_mfma_f32_16x16x32_bf16 v[100:103], v[144:147], v[196:199], v[100:103]
	v_mfma_f32_16x16x32_bf16 v[100:103], v[148:151], v[200:203], v[100:103]
	v_mfma_f32_16x16x32_bf16 v[84:87], v[148:151], v[212:215], v[84:87]
	v_mfma_f32_16x16x32_bf16 v[84:87], v[144:147], v[204:207], v[84:87]
	v_mfma_f32_16x16x32_bf16 v[80:83], v[152:155], v[204:207], v[80:83]
	v_mfma_f32_16x16x32_bf16 v[80:83], v[156:159], v[212:215], v[80:83]
	v_mfma_f32_16x16x32_bf16 v[96:99], v[156:159], v[200:203], v[96:99]
	v_mfma_f32_16x16x32_bf16 v[96:99], v[152:155], v[196:199], v[96:99]
	v_mfma_f32_16x16x32_bf16 v[112:115], v[152:155], v[188:191], v[112:115]
	v_mfma_f32_16x16x32_bf16 v[112:115], v[156:159], v[192:195], v[112:115]
	v_mfma_f32_16x16x32_bf16 v[120:123], v[156:159], v[184:187], v[120:123]
	v_mfma_f32_16x16x32_bf16 v[120:123], v[152:155], v[180:183], v[120:123]
	v_mfma_f32_16x16x32_bf16 v[108:111], v[160:163], v[180:183], v[108:111]
	v_mfma_f32_16x16x32_bf16 v[108:111], v[164:167], v[184:187], v[108:111]
	v_mfma_f32_16x16x32_bf16 v[92:95], v[164:167], v[192:195], v[92:95]
	v_mfma_f32_16x16x32_bf16 v[92:95], v[160:163], v[188:191], v[92:95]
	v_mfma_f32_16x16x32_bf16 v[76:79], v[160:163], v[196:199], v[76:79]
	v_mfma_f32_16x16x32_bf16 v[76:79], v[164:167], v[200:203], v[76:79]
	v_mfma_f32_16x16x32_bf16 v[68:71], v[164:167], v[212:215], v[68:71]
	v_mfma_f32_16x16x32_bf16 v[68:71], v[160:163], v[204:207], v[68:71]
	v_mfma_f32_16x16x32_bf16 v[64:67], v[172:175], v[204:207], v[64:67]
	v_mfma_f32_16x16x32_bf16 v[64:67], v[176:179], v[212:215], v[64:67]
	v_mfma_f32_16x16x32_bf16 v[72:75], v[176:179], v[200:203], v[72:75]
	v_mfma_f32_16x16x32_bf16 v[72:75], v[172:175], v[196:199], v[72:75]
	v_mfma_f32_16x16x32_bf16 v[88:91], v[172:175], v[188:191], v[88:91]
	v_mfma_f32_16x16x32_bf16 v[88:91], v[176:179], v[192:195], v[88:91]
	v_mfma_f32_16x16x32_bf16 v[104:107], v[176:179], v[184:187], v[104:107]
	v_mfma_f32_16x16x32_bf16 v[104:107], v[172:175], v[180:183], v[104:107]
	s_barrier
	s_add_i32 s56, s56, s38
	v_lshl_add_u64 v[218:219], v[208:209], 0, s[12:13]
	s_mov_b32 m0, s56
	s_nop 0
	global_load_lds_dwordx4 v[218:219], off
	v_lshl_add_u64 v[218:219], v[208:209], 0, s[14:15]
	s_add_i32 m0, s56, 0x2000
	s_add_i32 s56, s57, s38
	global_load_lds_dwordx4 v[218:219], off
	v_lshl_add_u64 v[218:219], v[208:209], 0, s[16:17]
	s_mov_b32 m0, s56
	v_lshl_add_u64 v[208:209], v[208:209], 0, s[18:19]
	global_load_lds_dwordx4 v[218:219], off
	s_add_i32 m0, s56, 0x2000
	s_nop 0
	global_load_lds_dwordx4 v[208:209], off
	v_lshl_add_u64 v[208:209], v[216:217], 0, s[12:13]
	s_mov_b32 m0, s44
	s_nop 0
	global_load_lds_dwordx4 v[208:209], off
	v_lshl_add_u64 v[208:209], v[216:217], 0, s[14:15]
	s_mov_b32 m0, s45
	s_nop 0
	global_load_lds_dwordx4 v[208:209], off
	ds_read_b128 v[180:183], v142 offset:49152
	ds_read_b128 v[184:187], v142 offset:50176
	ds_read_b128 v[188:191], v142 offset:51200
	ds_read_b128 v[192:195], v142 offset:52224
	ds_read_b128 v[196:199], v142 offset:53248
	ds_read_b128 v[200:203], v142 offset:54272
	ds_read_b128 v[204:207], v142 offset:55296
	ds_read_b128 v[212:215], v142 offset:56320
	s_waitcnt vmcnt(8)
	s_waitcnt lgkmcnt(0)
	s_barrier
	s_waitcnt lgkmcnt(0)
	v_mfma_f32_16x16x32_bf16 v[60:63], v[144:147], v[180:183], v[60:63]
	v_mfma_f32_16x16x32_bf16 v[60:63], v[148:151], v[184:187], v[60:63]
	v_mfma_f32_16x16x32_bf16 v[52:55], v[148:151], v[192:195], v[52:55]
	v_mfma_f32_16x16x32_bf16 v[52:55], v[144:147], v[188:191], v[52:55]
	v_mfma_f32_16x16x32_bf16 v[36:39], v[144:147], v[196:199], v[36:39]
	v_mfma_f32_16x16x32_bf16 v[36:39], v[148:151], v[200:203], v[36:39]
	v_mfma_f32_16x16x32_bf16 v[20:23], v[148:151], v[212:215], v[20:23]
	v_mfma_f32_16x16x32_bf16 v[20:23], v[144:147], v[204:207], v[20:23]
	v_mfma_f32_16x16x32_bf16 v[16:19], v[152:155], v[204:207], v[16:19]
	v_mfma_f32_16x16x32_bf16 v[16:19], v[156:159], v[212:215], v[16:19]
	v_mfma_f32_16x16x32_bf16 v[32:35], v[156:159], v[200:203], v[32:35]
	v_mfma_f32_16x16x32_bf16 v[32:35], v[152:155], v[196:199], v[32:35]
	v_mfma_f32_16x16x32_bf16 v[48:51], v[152:155], v[188:191], v[48:51]
	v_mfma_f32_16x16x32_bf16 v[48:51], v[156:159], v[192:195], v[48:51]
	v_mfma_f32_16x16x32_bf16 v[56:59], v[156:159], v[184:187], v[56:59]
	v_mfma_f32_16x16x32_bf16 v[56:59], v[152:155], v[180:183], v[56:59]
	v_mfma_f32_16x16x32_bf16 v[44:47], v[160:163], v[180:183], v[44:47]
	v_mfma_f32_16x16x32_bf16 v[44:47], v[164:167], v[184:187], v[44:47]
	v_mfma_f32_16x16x32_bf16 v[28:31], v[164:167], v[192:195], v[28:31]
	v_mfma_f32_16x16x32_bf16 v[28:31], v[160:163], v[188:191], v[28:31]
	v_mfma_f32_16x16x32_bf16 v[12:15], v[160:163], v[196:199], v[12:15]
	v_mfma_f32_16x16x32_bf16 v[12:15], v[164:167], v[200:203], v[12:15]
	v_mfma_f32_16x16x32_bf16 v[4:7], v[164:167], v[212:215], v[4:7]
	v_mfma_f32_16x16x32_bf16 v[4:7], v[160:163], v[204:207], v[4:7]
	v_mfma_f32_16x16x32_bf16 v[0:3], v[172:175], v[204:207], v[0:3]
	v_mfma_f32_16x16x32_bf16 v[0:3], v[176:179], v[212:215], v[0:3]
	v_mfma_f32_16x16x32_bf16 v[8:11], v[176:179], v[200:203], v[8:11]
	v_mfma_f32_16x16x32_bf16 v[8:11], v[172:175], v[196:199], v[8:11]
	v_mfma_f32_16x16x32_bf16 v[24:27], v[172:175], v[188:191], v[24:27]
	v_mfma_f32_16x16x32_bf16 v[24:27], v[176:179], v[192:195], v[24:27]
	v_mfma_f32_16x16x32_bf16 v[40:43], v[176:179], v[184:187], v[40:43]
	v_mfma_f32_16x16x32_bf16 v[40:43], v[172:175], v[180:183], v[40:43]
	s_barrier
	s_cmp_gt_u32 s55, 41
	s_cbranch_scc0 .LBB0_1046
	s_and_b64 vcc, exec, s[20:21]
	s_cbranch_vccz .LBB0_1049
	s_barrier
